# GEMM k-loop barrier moved to the first point where this wave's LDS traffic has drained (before the last 29 MFMAs), 15 instances
# baseline (speedup 1.0000x reference)
; #define LD_BF(dst, ks_, nh_) _Pragma("unroll") for (int i = 0; i < 4; ++i) dst[i] = *(const h8*)(sB + ((nh_) * 4 + i) * 16 * G_LD + (ks_) * 32)
; #define MMA_BLK(afx, bfx, nh_) _Pragma("unroll") for (int mi = 0; mi < 8; ++mi) _Pragma("unroll") for (int ni = 0; ni < 4; ++ni) mfma16_acc(acc[mi][(nh_) * 4 + ni], bfx[ni], afx[mi])
; template <class Epi>
; __device__ __forceinline__ void gemm_run(const GemmArgs g, Epi epi, char* smem) {
;     ...
;       LD_BF(bfB, 1, 1);
;       MMA_BLK(afB, bfA, 0);
;       __builtin_amdgcn_sched_barrier(0);
;       MMA_BLK(afB, bfB, 1);
;       __builtin_amdgcn_sched_barrier(0);
;     ...
;       __syncthreads();
;     }
.LBB0_196:
	ds_read_b128 v[4:7], v94 offset:46144
	ds_read_b128 v[32:35], v94 offset:48448
	ds_read_b128 v[40:43], v94 offset:50752
	ds_read_b128 v[44:47], v94 offset:53056
	s_waitcnt lgkmcnt(7)
	v_mfma_f32_16x16x32_f16 a[252:255], v[56:59], v[36:39], a[252:255]
	s_waitcnt lgkmcnt(6)
	v_mfma_f32_16x16x32_f16 a[240:243], v[60:63], v[36:39], a[240:243]
	s_waitcnt lgkmcnt(5)
	v_mfma_f32_16x16x32_f16 a[232:235], v[64:67], v[36:39], a[232:235]
	s_waitcnt lgkmcnt(4)
	v_mfma_f32_16x16x32_f16 a[224:227], v[68:71], v[36:39], a[224:227]
	v_mfma_f32_16x16x32_f16 a[216:219], v[56:59], v[28:31], a[216:219]
	v_mfma_f32_16x16x32_f16 a[208:211], v[60:63], v[28:31], a[208:211]
	v_mfma_f32_16x16x32_f16 a[200:203], v[64:67], v[28:31], a[200:203]
	v_mfma_f32_16x16x32_f16 a[192:195], v[68:71], v[28:31], a[192:195]
	v_mfma_f32_16x16x32_f16 a[184:187], v[56:59], v[24:27], a[184:187]
	v_mfma_f32_16x16x32_f16 a[176:179], v[60:63], v[24:27], a[176:179]
	v_mfma_f32_16x16x32_f16 a[168:171], v[64:67], v[24:27], a[168:171]
	v_mfma_f32_16x16x32_f16 a[160:163], v[68:71], v[24:27], a[160:163]
	v_mfma_f32_16x16x32_f16 a[152:155], v[56:59], v[20:23], a[152:155]
	v_mfma_f32_16x16x32_f16 a[144:147], v[60:63], v[20:23], a[144:147]
	v_mfma_f32_16x16x32_f16 a[136:139], v[64:67], v[20:23], a[136:139]
	v_mfma_f32_16x16x32_f16 a[128:131], v[68:71], v[20:23], a[128:131]
	v_mfma_f32_16x16x32_f16 a[120:123], v[56:59], v[16:19], a[120:123]
	v_mfma_f32_16x16x32_f16 a[112:115], v[60:63], v[16:19], a[112:115]
	v_mfma_f32_16x16x32_f16 a[104:107], v[64:67], v[16:19], a[104:107]
	v_mfma_f32_16x16x32_f16 a[96:99], v[68:71], v[16:19], a[96:99]
	v_mfma_f32_16x16x32_f16 a[88:91], v[56:59], v[12:15], a[88:91]
	v_mfma_f32_16x16x32_f16 a[80:83], v[60:63], v[12:15], a[80:83]
	v_mfma_f32_16x16x32_f16 a[72:75], v[64:67], v[12:15], a[72:75]
	v_mfma_f32_16x16x32_f16 a[64:67], v[68:71], v[12:15], a[64:67]
	v_mfma_f32_16x16x32_f16 a[56:59], v[56:59], v[8:11], a[56:59]
	v_mfma_f32_16x16x32_f16 a[48:51], v[60:63], v[8:11], a[48:51]
	v_mfma_f32_16x16x32_f16 a[40:43], v[64:67], v[8:11], a[40:43]
	v_mfma_f32_16x16x32_f16 a[32:35], v[68:71], v[8:11], a[32:35]
	v_mfma_f32_16x16x32_f16 a[24:27], v[56:59], v[0:3], a[24:27]
	v_mfma_f32_16x16x32_f16 a[20:23], v[60:63], v[0:3], a[20:23]
	v_mfma_f32_16x16x32_f16 a[16:19], v[64:67], v[0:3], a[16:19]
	v_mfma_f32_16x16x32_f16 a[8:11], v[68:71], v[0:3], a[8:11]
	s_waitcnt lgkmcnt(3)
	v_mfma_f32_16x16x32_f16 a[248:251], v[4:7], v[36:39], a[248:251]
	s_waitcnt lgkmcnt(2)
	v_mfma_f32_16x16x32_f16 a[244:247], v[32:35], v[36:39], a[244:247]
	s_waitcnt lgkmcnt(1)
	v_mfma_f32_16x16x32_f16 a[236:239], v[40:43], v[36:39], a[236:239]
	s_waitcnt lgkmcnt(0)
	s_barrier
	v_mfma_f32_16x16x32_f16 a[228:231], v[44:47], v[36:39], a[228:231]
	v_mfma_f32_16x16x32_f16 a[220:223], v[4:7], v[28:31], a[220:223]
	v_mfma_f32_16x16x32_f16 a[212:215], v[32:35], v[28:31], a[212:215]
	v_mfma_f32_16x16x32_f16 a[204:207], v[40:43], v[28:31], a[204:207]
	v_mfma_f32_16x16x32_f16 a[196:199], v[44:47], v[28:31], a[196:199]
	v_mfma_f32_16x16x32_f16 a[188:191], v[4:7], v[24:27], a[188:191]
	v_mfma_f32_16x16x32_f16 a[180:183], v[32:35], v[24:27], a[180:183]
	v_mfma_f32_16x16x32_f16 a[172:175], v[40:43], v[24:27], a[172:175]
	v_mfma_f32_16x16x32_f16 a[164:167], v[44:47], v[24:27], a[164:167]
	v_mfma_f32_16x16x32_f16 a[156:159], v[4:7], v[20:23], a[156:159]
	v_mfma_f32_16x16x32_f16 a[148:151], v[32:35], v[20:23], a[148:151]
	v_mfma_f32_16x16x32_f16 a[140:143], v[40:43], v[20:23], a[140:143]
	v_mfma_f32_16x16x32_f16 a[132:135], v[44:47], v[20:23], a[132:135]
	v_mfma_f32_16x16x32_f16 a[124:127], v[4:7], v[16:19], a[124:127]
	v_mfma_f32_16x16x32_f16 a[116:119], v[32:35], v[16:19], a[116:119]
	v_mfma_f32_16x16x32_f16 a[108:111], v[40:43], v[16:19], a[108:111]
	v_mfma_f32_16x16x32_f16 a[100:103], v[44:47], v[16:19], a[100:103]
	v_mfma_f32_16x16x32_f16 a[92:95], v[4:7], v[12:15], a[92:95]
	v_mfma_f32_16x16x32_f16 a[84:87], v[32:35], v[12:15], a[84:87]
	v_mfma_f32_16x16x32_f16 a[76:79], v[40:43], v[12:15], a[76:79]
	v_mfma_f32_16x16x32_f16 a[68:71], v[44:47], v[12:15], a[68:71]
	v_mfma_f32_16x16x32_f16 a[60:63], v[4:7], v[8:11], a[60:63]
	v_mfma_f32_16x16x32_f16 a[52:55], v[32:35], v[8:11], a[52:55]
	v_mfma_f32_16x16x32_f16 a[44:47], v[40:43], v[8:11], a[44:47]
	v_mfma_f32_16x16x32_f16 a[36:39], v[44:47], v[8:11], a[36:39]
	v_mfma_f32_16x16x32_f16 a[28:31], v[4:7], v[0:3], a[28:31]
	v_mfma_f32_16x16x32_f16 a[12:15], v[32:35], v[0:3], a[12:15]
	v_mfma_f32_16x16x32_f16 a[4:7], v[40:43], v[0:3], a[4:7]
	v_mfma_f32_16x16x32_f16 a[0:3], v[44:47], v[0:3], a[0:3]
	s_addk_i32 s9, 0x80
	s_cmp_eq_u32 s9, 0xe1080
	s_cbranch_scc1 .LBB0_199

; #define LD_BF(dst, ks_, nh_) _Pragma("unroll") for (int i = 0; i < 4; ++i) dst[i] = *(const h8*)(sB + ((nh_) * 4 + i) * 16 * G_LD + (ks_) * 32)
; #define MMA_BLK(afx, bfx, nh_) _Pragma("unroll") for (int mi = 0; mi < 8; ++mi) _Pragma("unroll") for (int ni = 0; ni < 4; ++ni) mfma16_acc(acc[mi][(nh_) * 4 + ni], bfx[ni], afx[mi])
; template <class Epi>
; __device__ __forceinline__ void gemm_run(const GemmArgs g, Epi epi, char* smem) {
;     ...
;       LD_BF(bfB, 1, 1);
;       MMA_BLK(afB, bfA, 0);
;       __builtin_amdgcn_sched_barrier(0);
;       MMA_BLK(afB, bfB, 1);
;       __builtin_amdgcn_sched_barrier(0);
;     ...
;       __syncthreads();
;     }
.LBB0_598:
	ds_read_b128 v[8:11], v106 offset:46144
	ds_read_b128 v[36:39], v106 offset:48448
	ds_read_b128 v[40:43], v106 offset:50752
	ds_read_b128 v[44:47], v106 offset:53056
	s_waitcnt lgkmcnt(7)
	v_mfma_f32_16x16x32_f16 a[0:3], v[56:59], v[32:35], a[0:3]
	s_waitcnt lgkmcnt(6)
	v_mfma_f32_16x16x32_f16 a[4:7], v[60:63], v[32:35], a[4:7]
	s_waitcnt lgkmcnt(5)
	v_mfma_f32_16x16x32_f16 a[8:11], v[64:67], v[32:35], a[8:11]
	s_waitcnt lgkmcnt(4)
	v_mfma_f32_16x16x32_f16 a[24:27], v[68:71], v[32:35], a[24:27]
	v_mfma_f32_16x16x32_f16 a[12:15], v[56:59], v[28:31], a[12:15]
	v_mfma_f32_16x16x32_f16 a[16:19], v[60:63], v[28:31], a[16:19]
	v_mfma_f32_16x16x32_f16 a[28:31], v[64:67], v[28:31], a[28:31]
	v_mfma_f32_16x16x32_f16 a[44:47], v[68:71], v[28:31], a[44:47]
	v_mfma_f32_16x16x32_f16 a[20:23], v[56:59], v[24:27], a[20:23]
	v_mfma_f32_16x16x32_f16 a[36:39], v[60:63], v[24:27], a[36:39]
	v_mfma_f32_16x16x32_f16 a[48:51], v[64:67], v[24:27], a[48:51]
	v_mfma_f32_16x16x32_f16 a[60:63], v[68:71], v[24:27], a[60:63]
	v_mfma_f32_16x16x32_f16 a[32:35], v[56:59], v[20:23], a[32:35]
	v_mfma_f32_16x16x32_f16 a[52:55], v[60:63], v[20:23], a[52:55]
	v_mfma_f32_16x16x32_f16 a[64:67], v[64:67], v[20:23], a[64:67]
	v_mfma_f32_16x16x32_f16 a[76:79], v[68:71], v[20:23], a[76:79]
	v_mfma_f32_16x16x32_f16 a[40:43], v[56:59], v[16:19], a[40:43]
	v_mfma_f32_16x16x32_f16 a[68:71], v[60:63], v[16:19], a[68:71]
	v_mfma_f32_16x16x32_f16 a[80:83], v[64:67], v[16:19], a[80:83]
	v_mfma_f32_16x16x32_f16 a[92:95], v[68:71], v[16:19], a[92:95]
	v_mfma_f32_16x16x32_f16 a[56:59], v[56:59], v[12:15], a[56:59]
	v_mfma_f32_16x16x32_f16 a[84:87], v[60:63], v[12:15], a[84:87]
	v_mfma_f32_16x16x32_f16 a[96:99], v[64:67], v[12:15], a[96:99]
	v_mfma_f32_16x16x32_f16 a[104:107], v[68:71], v[12:15], a[104:107]
	v_mfma_f32_16x16x32_f16 a[72:75], v[56:59], v[4:7], a[72:75]
	v_mfma_f32_16x16x32_f16 a[100:103], v[60:63], v[4:7], a[100:103]
	v_mfma_f32_16x16x32_f16 a[108:111], v[64:67], v[4:7], a[108:111]
	v_mfma_f32_16x16x32_f16 a[124:127], v[68:71], v[4:7], a[124:127]
	v_mfma_f32_16x16x32_f16 a[88:91], v[56:59], v[0:3], a[88:91]
	v_mfma_f32_16x16x32_f16 a[112:115], v[60:63], v[0:3], a[112:115]
	v_mfma_f32_16x16x32_f16 a[116:119], v[64:67], v[0:3], a[116:119]
	v_mfma_f32_16x16x32_f16 a[120:123], v[68:71], v[0:3], a[120:123]
	s_waitcnt lgkmcnt(3)
	v_mfma_f32_16x16x32_f16 a[132:135], v[8:11], v[32:35], a[132:135]
	s_waitcnt lgkmcnt(2)
	v_mfma_f32_16x16x32_f16 a[136:139], v[36:39], v[32:35], a[136:139]
	s_waitcnt lgkmcnt(1)
	v_mfma_f32_16x16x32_f16 a[144:147], v[40:43], v[32:35], a[144:147]
	s_waitcnt lgkmcnt(0)
	s_barrier
	v_mfma_f32_16x16x32_f16 a[156:159], v[44:47], v[32:35], a[156:159]
	v_mfma_f32_16x16x32_f16 a[140:143], v[8:11], v[28:31], a[140:143]
	v_mfma_f32_16x16x32_f16 a[148:151], v[36:39], v[28:31], a[148:151]
	v_mfma_f32_16x16x32_f16 a[164:167], v[40:43], v[28:31], a[164:167]
	v_mfma_f32_16x16x32_f16 a[184:187], v[44:47], v[28:31], a[184:187]
	v_mfma_f32_16x16x32_f16 a[152:155], v[8:11], v[24:27], a[152:155]
	v_mfma_f32_16x16x32_f16 a[168:171], v[36:39], v[24:27], a[168:171]
	v_mfma_f32_16x16x32_f16 a[180:183], v[40:43], v[24:27], a[180:183]
	v_mfma_f32_16x16x32_f16 a[200:203], v[44:47], v[24:27], a[200:203]
	v_mfma_f32_16x16x32_f16 a[160:163], v[8:11], v[20:23], a[160:163]
	v_mfma_f32_16x16x32_f16 a[176:179], v[36:39], v[20:23], a[176:179]
	v_mfma_f32_16x16x32_f16 a[196:199], v[40:43], v[20:23], a[196:199]
	v_mfma_f32_16x16x32_f16 a[216:219], v[44:47], v[20:23], a[216:219]
	v_mfma_f32_16x16x32_f16 a[172:175], v[8:11], v[16:19], a[172:175]
	v_mfma_f32_16x16x32_f16 a[192:195], v[36:39], v[16:19], a[192:195]
	v_mfma_f32_16x16x32_f16 a[212:215], v[40:43], v[16:19], a[212:215]
	v_mfma_f32_16x16x32_f16 a[232:235], v[44:47], v[16:19], a[232:235]
	v_mfma_f32_16x16x32_f16 a[188:191], v[8:11], v[12:15], a[188:191]
	v_mfma_f32_16x16x32_f16 a[208:211], v[36:39], v[12:15], a[208:211]
	v_mfma_f32_16x16x32_f16 a[228:231], v[40:43], v[12:15], a[228:231]
	v_mfma_f32_16x16x32_f16 a[244:247], v[44:47], v[12:15], a[244:247]
	v_mfma_f32_16x16x32_f16 a[204:207], v[8:11], v[4:7], a[204:207]
	v_mfma_f32_16x16x32_f16 a[224:227], v[36:39], v[4:7], a[224:227]
	v_mfma_f32_16x16x32_f16 a[240:243], v[40:43], v[4:7], a[240:243]
	v_mfma_f32_16x16x32_f16 a[252:255], v[44:47], v[4:7], a[252:255]
	v_mfma_f32_16x16x32_f16 a[220:223], v[8:11], v[0:3], a[220:223]
	v_mfma_f32_16x16x32_f16 a[236:239], v[36:39], v[0:3], a[236:239]
	v_mfma_f32_16x16x32_f16 a[248:251], v[40:43], v[0:3], a[248:251]
	v_mfma_f32_16x16x32_f16 a[128:131], v[44:47], v[0:3], a[128:131]
	s_addk_i32 s15, 0x80
	s_cmp_eq_u32 s15, 0x54480
	s_cbranch_scc1 .LBB0_596

; #define LD_BF(dst, ks_, nh_) _Pragma("unroll") for (int i = 0; i < 4; ++i) dst[i] = *(const h8*)(sB + ((nh_) * 4 + i) * 16 * G_LD + (ks_) * 32)
; #define MMA_BLK(afx, bfx, nh_) _Pragma("unroll") for (int mi = 0; mi < 8; ++mi) _Pragma("unroll") for (int ni = 0; ni < 4; ++ni) mfma16_acc(acc[mi][(nh_) * 4 + ni], bfx[ni], afx[mi])
; template <class Epi>
; __device__ __forceinline__ void gemm_run(const GemmArgs g, Epi epi, char* smem) {
;     ...
;       LD_BF(bfB, 1, 1);
;       MMA_BLK(afB, bfA, 0);
;       __builtin_amdgcn_sched_barrier(0);
;       MMA_BLK(afB, bfB, 1);
;       __builtin_amdgcn_sched_barrier(0);
;     ...
;       __syncthreads();
;     }
.LBB0_630:
	ds_read_b128 v[4:7], v94 offset:46144
	ds_read_b128 v[32:35], v94 offset:48448
	ds_read_b128 v[40:43], v94 offset:50752
	ds_read_b128 v[44:47], v94 offset:53056
	s_waitcnt lgkmcnt(7)
	v_mfma_f32_16x16x32_f16 a[252:255], v[56:59], v[36:39], a[252:255]
	s_waitcnt lgkmcnt(6)
	v_mfma_f32_16x16x32_f16 a[248:251], v[60:63], v[36:39], a[248:251]
	s_waitcnt lgkmcnt(5)
	v_mfma_f32_16x16x32_f16 a[244:247], v[64:67], v[36:39], a[244:247]
	s_waitcnt lgkmcnt(4)
	v_mfma_f32_16x16x32_f16 a[236:239], v[68:71], v[36:39], a[236:239]
	v_mfma_f32_16x16x32_f16 a[220:223], v[56:59], v[28:31], a[220:223]
	v_mfma_f32_16x16x32_f16 a[216:219], v[60:63], v[28:31], a[216:219]
	v_mfma_f32_16x16x32_f16 a[212:215], v[64:67], v[28:31], a[212:215]
	v_mfma_f32_16x16x32_f16 a[204:207], v[68:71], v[28:31], a[204:207]
	v_mfma_f32_16x16x32_f16 a[188:191], v[56:59], v[24:27], a[188:191]
	v_mfma_f32_16x16x32_f16 a[184:187], v[60:63], v[24:27], a[184:187]
	v_mfma_f32_16x16x32_f16 a[180:183], v[64:67], v[24:27], a[180:183]
	v_mfma_f32_16x16x32_f16 a[172:175], v[68:71], v[24:27], a[172:175]
	v_mfma_f32_16x16x32_f16 a[156:159], v[56:59], v[20:23], a[156:159]
	v_mfma_f32_16x16x32_f16 a[152:155], v[60:63], v[20:23], a[152:155]
	v_mfma_f32_16x16x32_f16 a[148:151], v[64:67], v[20:23], a[148:151]
	v_mfma_f32_16x16x32_f16 a[140:143], v[68:71], v[20:23], a[140:143]
	v_mfma_f32_16x16x32_f16 a[124:127], v[56:59], v[16:19], a[124:127]
	v_mfma_f32_16x16x32_f16 a[120:123], v[60:63], v[16:19], a[120:123]
	v_mfma_f32_16x16x32_f16 a[116:119], v[64:67], v[16:19], a[116:119]
	v_mfma_f32_16x16x32_f16 a[108:111], v[68:71], v[16:19], a[108:111]
	v_mfma_f32_16x16x32_f16 a[92:95], v[56:59], v[12:15], a[92:95]
	v_mfma_f32_16x16x32_f16 a[88:91], v[60:63], v[12:15], a[88:91]
	v_mfma_f32_16x16x32_f16 a[84:87], v[64:67], v[12:15], a[84:87]
	v_mfma_f32_16x16x32_f16 a[76:79], v[68:71], v[12:15], a[76:79]
	v_mfma_f32_16x16x32_f16 a[60:63], v[56:59], v[8:11], a[60:63]
	v_mfma_f32_16x16x32_f16 a[56:59], v[60:63], v[8:11], a[56:59]
	v_mfma_f32_16x16x32_f16 a[52:55], v[64:67], v[8:11], a[52:55]
	v_mfma_f32_16x16x32_f16 a[44:47], v[68:71], v[8:11], a[44:47]
	v_mfma_f32_16x16x32_f16 a[28:31], v[56:59], v[0:3], a[28:31]
	v_mfma_f32_16x16x32_f16 a[24:27], v[60:63], v[0:3], a[24:27]
	v_mfma_f32_16x16x32_f16 a[20:23], v[64:67], v[0:3], a[20:23]
	v_mfma_f32_16x16x32_f16 a[12:15], v[68:71], v[0:3], a[12:15]
	s_waitcnt lgkmcnt(3)
	v_mfma_f32_16x16x32_f16 a[240:243], v[4:7], v[36:39], a[240:243]
	s_waitcnt lgkmcnt(2)
	v_mfma_f32_16x16x32_f16 a[232:235], v[32:35], v[36:39], a[232:235]
	s_waitcnt lgkmcnt(1)
	v_mfma_f32_16x16x32_f16 a[228:231], v[40:43], v[36:39], a[228:231]
	s_waitcnt lgkmcnt(0)
	s_barrier
	v_mfma_f32_16x16x32_f16 a[224:227], v[44:47], v[36:39], a[224:227]
	v_mfma_f32_16x16x32_f16 a[208:211], v[4:7], v[28:31], a[208:211]
	v_mfma_f32_16x16x32_f16 a[200:203], v[32:35], v[28:31], a[200:203]
	v_mfma_f32_16x16x32_f16 a[196:199], v[40:43], v[28:31], a[196:199]
	v_mfma_f32_16x16x32_f16 a[192:195], v[44:47], v[28:31], a[192:195]
	v_mfma_f32_16x16x32_f16 a[176:179], v[4:7], v[24:27], a[176:179]
	v_mfma_f32_16x16x32_f16 a[168:171], v[32:35], v[24:27], a[168:171]
	v_mfma_f32_16x16x32_f16 a[164:167], v[40:43], v[24:27], a[164:167]
	v_mfma_f32_16x16x32_f16 a[160:163], v[44:47], v[24:27], a[160:163]
	v_mfma_f32_16x16x32_f16 a[144:147], v[4:7], v[20:23], a[144:147]
	v_mfma_f32_16x16x32_f16 a[136:139], v[32:35], v[20:23], a[136:139]
	v_mfma_f32_16x16x32_f16 a[132:135], v[40:43], v[20:23], a[132:135]
	v_mfma_f32_16x16x32_f16 a[128:131], v[44:47], v[20:23], a[128:131]
	v_mfma_f32_16x16x32_f16 a[112:115], v[4:7], v[16:19], a[112:115]
	v_mfma_f32_16x16x32_f16 a[104:107], v[32:35], v[16:19], a[104:107]
	v_mfma_f32_16x16x32_f16 a[100:103], v[40:43], v[16:19], a[100:103]
	v_mfma_f32_16x16x32_f16 a[96:99], v[44:47], v[16:19], a[96:99]
	v_mfma_f32_16x16x32_f16 a[80:83], v[4:7], v[12:15], a[80:83]
	v_mfma_f32_16x16x32_f16 a[72:75], v[32:35], v[12:15], a[72:75]
	v_mfma_f32_16x16x32_f16 a[68:71], v[40:43], v[12:15], a[68:71]
	v_mfma_f32_16x16x32_f16 a[64:67], v[44:47], v[12:15], a[64:67]
	v_mfma_f32_16x16x32_f16 a[48:51], v[4:7], v[8:11], a[48:51]
	v_mfma_f32_16x16x32_f16 a[40:43], v[32:35], v[8:11], a[40:43]
	v_mfma_f32_16x16x32_f16 a[36:39], v[40:43], v[8:11], a[36:39]
	v_mfma_f32_16x16x32_f16 a[32:35], v[44:47], v[8:11], a[32:35]
	v_mfma_f32_16x16x32_f16 a[16:19], v[4:7], v[0:3], a[16:19]
	v_mfma_f32_16x16x32_f16 a[8:11], v[32:35], v[0:3], a[8:11]
	v_mfma_f32_16x16x32_f16 a[4:7], v[40:43], v[0:3], a[4:7]
	v_mfma_f32_16x16x32_f16 a[0:3], v[44:47], v[0:3], a[0:3]
	s_addk_i32 s74, 0x80
	s_cmp_eq_u32 s74, 0x54680
	s_cbranch_scc1 .LBB0_628

; #define LD_BF(dst, ks_, nh_) _Pragma("unroll") for (int i = 0; i < 4; ++i) dst[i] = *(const h8*)(sB + ((nh_) * 4 + i) * 16 * G_LD + (ks_) * 32)
; #define MMA_BLK(afx, bfx, nh_) _Pragma("unroll") for (int mi = 0; mi < 8; ++mi) _Pragma("unroll") for (int ni = 0; ni < 4; ++ni) mfma16_acc(acc[mi][(nh_) * 4 + ni], bfx[ni], afx[mi])
; template <class Epi>
; __device__ __forceinline__ void gemm_run(const GemmArgs g, Epi epi, char* smem) {
;     ...
;       LD_BF(bfB, 1, 1);
;       MMA_BLK(afB, bfA, 0);
;       __builtin_amdgcn_sched_barrier(0);
;       MMA_BLK(afB, bfB, 1);
;       __builtin_amdgcn_sched_barrier(0);
;     ...
;       __syncthreads();
;     }
.LBB0_647:
	ds_read_b128 v[4:7], v104 offset:46144
	ds_read_b128 v[32:35], v104 offset:48448
	ds_read_b128 v[40:43], v104 offset:50752
	ds_read_b128 v[44:47], v104 offset:53056
	s_waitcnt lgkmcnt(7)
	v_mfma_f32_16x16x32_f16 a[252:255], v[56:59], v[36:39], a[252:255]
	s_waitcnt lgkmcnt(6)
	v_mfma_f32_16x16x32_f16 a[248:251], v[60:63], v[36:39], a[248:251]
	s_waitcnt lgkmcnt(5)
	v_mfma_f32_16x16x32_f16 a[244:247], v[64:67], v[36:39], a[244:247]
	s_waitcnt lgkmcnt(4)
	v_mfma_f32_16x16x32_f16 a[240:243], v[68:71], v[36:39], a[240:243]
	v_mfma_f32_16x16x32_f16 a[220:223], v[56:59], v[28:31], a[220:223]
	v_mfma_f32_16x16x32_f16 a[216:219], v[60:63], v[28:31], a[216:219]
	v_mfma_f32_16x16x32_f16 a[212:215], v[64:67], v[28:31], a[212:215]
	v_mfma_f32_16x16x32_f16 a[208:211], v[68:71], v[28:31], a[208:211]
	v_mfma_f32_16x16x32_f16 a[188:191], v[56:59], v[24:27], a[188:191]
	v_mfma_f32_16x16x32_f16 a[184:187], v[60:63], v[24:27], a[184:187]
	v_mfma_f32_16x16x32_f16 a[180:183], v[64:67], v[24:27], a[180:183]
	v_mfma_f32_16x16x32_f16 a[176:179], v[68:71], v[24:27], a[176:179]
	v_mfma_f32_16x16x32_f16 a[156:159], v[56:59], v[20:23], a[156:159]
	v_mfma_f32_16x16x32_f16 a[152:155], v[60:63], v[20:23], a[152:155]
	v_mfma_f32_16x16x32_f16 a[148:151], v[64:67], v[20:23], a[148:151]
	v_mfma_f32_16x16x32_f16 a[144:147], v[68:71], v[20:23], a[144:147]
	v_mfma_f32_16x16x32_f16 a[124:127], v[56:59], v[16:19], a[124:127]
	v_mfma_f32_16x16x32_f16 a[120:123], v[60:63], v[16:19], a[120:123]
	v_mfma_f32_16x16x32_f16 a[116:119], v[64:67], v[16:19], a[116:119]
	v_mfma_f32_16x16x32_f16 a[112:115], v[68:71], v[16:19], a[112:115]
	v_mfma_f32_16x16x32_f16 a[92:95], v[56:59], v[12:15], a[92:95]
	v_mfma_f32_16x16x32_f16 a[88:91], v[60:63], v[12:15], a[88:91]
	v_mfma_f32_16x16x32_f16 a[84:87], v[64:67], v[12:15], a[84:87]
	v_mfma_f32_16x16x32_f16 a[80:83], v[68:71], v[12:15], a[80:83]
	v_mfma_f32_16x16x32_f16 a[60:63], v[56:59], v[8:11], a[60:63]
	v_mfma_f32_16x16x32_f16 a[56:59], v[60:63], v[8:11], a[56:59]
	v_mfma_f32_16x16x32_f16 a[52:55], v[64:67], v[8:11], a[52:55]
	v_mfma_f32_16x16x32_f16 a[48:51], v[68:71], v[8:11], a[48:51]
	v_mfma_f32_16x16x32_f16 a[28:31], v[56:59], v[0:3], a[28:31]
	v_mfma_f32_16x16x32_f16 a[24:27], v[60:63], v[0:3], a[24:27]
	v_mfma_f32_16x16x32_f16 a[20:23], v[64:67], v[0:3], a[20:23]
	v_mfma_f32_16x16x32_f16 a[16:19], v[68:71], v[0:3], a[16:19]
	s_waitcnt lgkmcnt(3)
	v_mfma_f32_16x16x32_f16 a[236:239], v[4:7], v[36:39], a[236:239]
	s_waitcnt lgkmcnt(2)
	v_mfma_f32_16x16x32_f16 a[232:235], v[32:35], v[36:39], a[232:235]
	s_waitcnt lgkmcnt(1)
	v_mfma_f32_16x16x32_f16 a[228:231], v[40:43], v[36:39], a[228:231]
	s_waitcnt lgkmcnt(0)
	s_barrier
	v_mfma_f32_16x16x32_f16 a[224:227], v[44:47], v[36:39], a[224:227]
	v_mfma_f32_16x16x32_f16 a[204:207], v[4:7], v[28:31], a[204:207]
	v_mfma_f32_16x16x32_f16 a[200:203], v[32:35], v[28:31], a[200:203]
	v_mfma_f32_16x16x32_f16 a[196:199], v[40:43], v[28:31], a[196:199]
	v_mfma_f32_16x16x32_f16 a[192:195], v[44:47], v[28:31], a[192:195]
	v_mfma_f32_16x16x32_f16 a[172:175], v[4:7], v[24:27], a[172:175]
	v_mfma_f32_16x16x32_f16 a[168:171], v[32:35], v[24:27], a[168:171]
	v_mfma_f32_16x16x32_f16 a[164:167], v[40:43], v[24:27], a[164:167]
	v_mfma_f32_16x16x32_f16 a[160:163], v[44:47], v[24:27], a[160:163]
	v_mfma_f32_16x16x32_f16 a[140:143], v[4:7], v[20:23], a[140:143]
	v_mfma_f32_16x16x32_f16 a[136:139], v[32:35], v[20:23], a[136:139]
	v_mfma_f32_16x16x32_f16 a[132:135], v[40:43], v[20:23], a[132:135]
	v_mfma_f32_16x16x32_f16 a[128:131], v[44:47], v[20:23], a[128:131]
	v_mfma_f32_16x16x32_f16 a[108:111], v[4:7], v[16:19], a[108:111]
	v_mfma_f32_16x16x32_f16 a[104:107], v[32:35], v[16:19], a[104:107]
	v_mfma_f32_16x16x32_f16 a[100:103], v[40:43], v[16:19], a[100:103]
	v_mfma_f32_16x16x32_f16 a[96:99], v[44:47], v[16:19], a[96:99]
	v_mfma_f32_16x16x32_f16 a[76:79], v[4:7], v[12:15], a[76:79]
	v_mfma_f32_16x16x32_f16 a[72:75], v[32:35], v[12:15], a[72:75]
	v_mfma_f32_16x16x32_f16 a[68:71], v[40:43], v[12:15], a[68:71]
	v_mfma_f32_16x16x32_f16 a[64:67], v[44:47], v[12:15], a[64:67]
	v_mfma_f32_16x16x32_f16 a[44:47], v[4:7], v[8:11], a[44:47]
	v_mfma_f32_16x16x32_f16 a[40:43], v[32:35], v[8:11], a[40:43]
	v_mfma_f32_16x16x32_f16 a[36:39], v[40:43], v[8:11], a[36:39]
	v_mfma_f32_16x16x32_f16 a[32:35], v[44:47], v[8:11], a[32:35]
	v_mfma_f32_16x16x32_f16 a[12:15], v[4:7], v[0:3], a[12:15]
	v_mfma_f32_16x16x32_f16 a[8:11], v[32:35], v[0:3], a[8:11]
	v_mfma_f32_16x16x32_f16 a[4:7], v[40:43], v[0:3], a[4:7]
	v_mfma_f32_16x16x32_f16 a[0:3], v[44:47], v[0:3], a[0:3]
	s_addk_i32 s3, 0x80
	s_cmp_eq_u32 s3, 0x70880
	s_cbranch_scc1 .LBB0_645

; #define LD_BF(dst, ks_, nh_) _Pragma("unroll") for (int i = 0; i < 4; ++i) dst[i] = *(const h8*)(sB + ((nh_) * 4 + i) * 16 * G_LD + (ks_) * 32)
; #define MMA_BLK(afx, bfx, nh_) _Pragma("unroll") for (int mi = 0; mi < 8; ++mi) _Pragma("unroll") for (int ni = 0; ni < 4; ++ni) mfma16_acc(acc[mi][(nh_) * 4 + ni], bfx[ni], afx[mi])
; template <class Epi>
; __device__ __forceinline__ void gemm_run(const GemmArgs g, Epi epi, char* smem) {
;     ...
;       LD_BF(bfB, 1, 1);
;       MMA_BLK(afB, bfA, 0);
;       __builtin_amdgcn_sched_barrier(0);
;       MMA_BLK(afB, bfB, 1);
;       __builtin_amdgcn_sched_barrier(0);
;     ...
;       __syncthreads();
;     }
.LBB0_920:
	ds_read_b128 v[0:3], v92 offset:46144
	ds_read_b128 v[20:23], v92 offset:48448
	ds_read_b128 v[36:39], v92 offset:50752
	ds_read_b128 v[40:43], v92 offset:53056
	s_waitcnt lgkmcnt(7)
	v_mfma_f32_16x16x32_f16 a[208:211], v[56:59], v[44:47], a[208:211]
	s_waitcnt lgkmcnt(6)
	v_mfma_f32_16x16x32_f16 a[200:203], v[60:63], v[44:47], a[200:203]
	s_waitcnt lgkmcnt(5)
	v_mfma_f32_16x16x32_f16 a[196:199], v[64:67], v[44:47], a[196:199]
	s_waitcnt lgkmcnt(4)
	v_mfma_f32_16x16x32_f16 a[192:195], v[68:71], v[44:47], a[192:195]
	v_mfma_f32_16x16x32_f16 a[188:191], v[56:59], v[32:35], a[188:191]
	v_mfma_f32_16x16x32_f16 a[184:187], v[60:63], v[32:35], a[184:187]
	v_mfma_f32_16x16x32_f16 a[180:183], v[64:67], v[32:35], a[180:183]
	v_mfma_f32_16x16x32_f16 a[176:179], v[68:71], v[32:35], a[176:179]
	v_mfma_f32_16x16x32_f16 a[156:159], v[56:59], v[28:31], a[156:159]
	v_mfma_f32_16x16x32_f16 a[152:155], v[60:63], v[28:31], a[152:155]
	v_mfma_f32_16x16x32_f16 a[148:151], v[64:67], v[28:31], a[148:151]
	v_mfma_f32_16x16x32_f16 a[144:147], v[68:71], v[28:31], a[144:147]
	v_mfma_f32_16x16x32_f16 a[124:127], v[56:59], v[24:27], a[124:127]
	v_mfma_f32_16x16x32_f16 a[120:123], v[60:63], v[24:27], a[120:123]
	v_mfma_f32_16x16x32_f16 a[116:119], v[64:67], v[24:27], a[116:119]
	v_mfma_f32_16x16x32_f16 a[112:115], v[68:71], v[24:27], a[112:115]
	v_mfma_f32_16x16x32_f16 a[92:95], v[56:59], v[16:19], a[92:95]
	v_mfma_f32_16x16x32_f16 a[88:91], v[60:63], v[16:19], a[88:91]
	v_mfma_f32_16x16x32_f16 a[84:87], v[64:67], v[16:19], a[84:87]
	v_mfma_f32_16x16x32_f16 a[80:83], v[68:71], v[16:19], a[80:83]
	v_mfma_f32_16x16x32_f16 a[60:63], v[56:59], v[12:15], a[60:63]
	v_mfma_f32_16x16x32_f16 a[56:59], v[60:63], v[12:15], a[56:59]
	v_mfma_f32_16x16x32_f16 a[52:55], v[64:67], v[12:15], a[52:55]
	v_mfma_f32_16x16x32_f16 a[48:51], v[68:71], v[12:15], a[48:51]
	v_mfma_f32_16x16x32_f16 a[32:35], v[56:59], v[8:11], a[32:35]
	v_mfma_f32_16x16x32_f16 a[28:31], v[60:63], v[8:11], a[28:31]
	v_mfma_f32_16x16x32_f16 a[24:27], v[64:67], v[8:11], a[24:27]
	v_mfma_f32_16x16x32_f16 a[20:23], v[68:71], v[8:11], a[20:23]
	v_mfma_f32_16x16x32_f16 a[12:15], v[56:59], v[4:7], a[12:15]
	v_mfma_f32_16x16x32_f16 a[8:11], v[60:63], v[4:7], a[8:11]
	v_mfma_f32_16x16x32_f16 a[4:7], v[64:67], v[4:7], a[4:7]
	v_mfma_f32_16x16x32_f16 a[0:3], v[68:71], v[4:7], a[0:3]
	s_waitcnt lgkmcnt(3)
	v_mfma_f32_16x16x32_f16 a[240:243], v[0:3], v[44:47], a[240:243]
	s_waitcnt lgkmcnt(2)
	v_mfma_f32_16x16x32_f16 a[252:255], v[20:23], v[44:47], a[252:255]
	s_waitcnt lgkmcnt(1)
	v_mfma_f32_16x16x32_f16 a[248:251], v[36:39], v[44:47], a[248:251]
	s_waitcnt lgkmcnt(0)
	s_barrier
	v_mfma_f32_16x16x32_f16 a[244:247], v[40:43], v[44:47], a[244:247]
	v_mfma_f32_16x16x32_f16 a[236:239], v[0:3], v[32:35], a[236:239]
	v_mfma_f32_16x16x32_f16 a[232:235], v[20:23], v[32:35], a[232:235]
	v_mfma_f32_16x16x32_f16 a[228:231], v[36:39], v[32:35], a[228:231]
	v_mfma_f32_16x16x32_f16 a[224:227], v[40:43], v[32:35], a[224:227]
	v_mfma_f32_16x16x32_f16 a[220:223], v[0:3], v[28:31], a[220:223]
	v_mfma_f32_16x16x32_f16 a[216:219], v[20:23], v[28:31], a[216:219]
	v_mfma_f32_16x16x32_f16 a[212:215], v[36:39], v[28:31], a[212:215]
	v_mfma_f32_16x16x32_f16 a[204:207], v[40:43], v[28:31], a[204:207]
	v_mfma_f32_16x16x32_f16 a[172:175], v[0:3], v[24:27], a[172:175]
	v_mfma_f32_16x16x32_f16 a[168:171], v[20:23], v[24:27], a[168:171]
	v_mfma_f32_16x16x32_f16 a[164:167], v[36:39], v[24:27], a[164:167]
	v_mfma_f32_16x16x32_f16 a[160:163], v[40:43], v[24:27], a[160:163]
	v_mfma_f32_16x16x32_f16 a[140:143], v[0:3], v[16:19], a[140:143]
	v_mfma_f32_16x16x32_f16 a[136:139], v[20:23], v[16:19], a[136:139]
	v_mfma_f32_16x16x32_f16 a[132:135], v[36:39], v[16:19], a[132:135]
	v_mfma_f32_16x16x32_f16 a[128:131], v[40:43], v[16:19], a[128:131]
	v_mfma_f32_16x16x32_f16 a[108:111], v[0:3], v[12:15], a[108:111]
	v_mfma_f32_16x16x32_f16 a[104:107], v[20:23], v[12:15], a[104:107]
	v_mfma_f32_16x16x32_f16 a[100:103], v[36:39], v[12:15], a[100:103]
	v_mfma_f32_16x16x32_f16 a[96:99], v[40:43], v[12:15], a[96:99]
	v_mfma_f32_16x16x32_f16 a[76:79], v[0:3], v[8:11], a[76:79]
	v_mfma_f32_16x16x32_f16 a[72:75], v[20:23], v[8:11], a[72:75]
	v_mfma_f32_16x16x32_f16 a[68:71], v[36:39], v[8:11], a[68:71]
	v_mfma_f32_16x16x32_f16 a[64:67], v[40:43], v[8:11], a[64:67]
	v_mfma_f32_16x16x32_f16 a[44:47], v[0:3], v[4:7], a[44:47]
	v_mfma_f32_16x16x32_f16 a[40:43], v[20:23], v[4:7], a[40:43]
	v_mfma_f32_16x16x32_f16 a[36:39], v[36:39], v[4:7], a[36:39]
	v_mfma_f32_16x16x32_f16 a[16:19], v[40:43], v[4:7], a[16:19]
	s_addk_i32 s19, 0x80
	s_cmp_eq_u32 s19, 0xe1080
	s_cbranch_scc1 .LBB0_918

; #define LD_BF(dst, ks_, nh_) _Pragma("unroll") for (int i = 0; i < 4; ++i) dst[i] = *(const h8*)(sB + ((nh_) * 4 + i) * 16 * G_LD + (ks_) * 32)
; #define MMA_BLK(afx, bfx, nh_) _Pragma("unroll") for (int mi = 0; mi < 8; ++mi) _Pragma("unroll") for (int ni = 0; ni < 4; ++ni) mfma16_acc(acc[mi][(nh_) * 4 + ni], bfx[ni], afx[mi])
; template <class Epi>
; __device__ __forceinline__ void gemm_run(const GemmArgs g, Epi epi, char* smem) {
;     ...
;       LD_BF(bfB, 1, 1);
;       MMA_BLK(afB, bfA, 0);
;       __builtin_amdgcn_sched_barrier(0);
;       MMA_BLK(afB, bfB, 1);
;       __builtin_amdgcn_sched_barrier(0);
;     ...
;       __syncthreads();
;     }
.LBB0_949:
	ds_read_b128 v[0:3], v106 offset:46144
	ds_read_b128 v[20:23], v106 offset:48448
	ds_read_b128 v[36:39], v106 offset:50752
	ds_read_b128 v[40:43], v106 offset:53056
	s_waitcnt lgkmcnt(7)
	v_mfma_f32_16x16x32_f16 a[120:123], v[56:59], v[44:47], a[120:123]
	s_waitcnt lgkmcnt(6)
	v_mfma_f32_16x16x32_f16 a[116:119], v[60:63], v[44:47], a[116:119]
	s_waitcnt lgkmcnt(5)
	v_mfma_f32_16x16x32_f16 a[112:115], v[64:67], v[44:47], a[112:115]
	s_waitcnt lgkmcnt(4)
	v_mfma_f32_16x16x32_f16 a[160:163], v[68:71], v[44:47], a[160:163]
	v_mfma_f32_16x16x32_f16 a[152:155], v[56:59], v[32:35], a[152:155]
	v_mfma_f32_16x16x32_f16 a[148:151], v[60:63], v[32:35], a[148:151]
	v_mfma_f32_16x16x32_f16 a[144:147], v[64:67], v[32:35], a[144:147]
	v_mfma_f32_16x16x32_f16 a[136:139], v[68:71], v[32:35], a[136:139]
	v_mfma_f32_16x16x32_f16 a[108:111], v[56:59], v[28:31], a[108:111]
	v_mfma_f32_16x16x32_f16 a[104:107], v[60:63], v[28:31], a[104:107]
	v_mfma_f32_16x16x32_f16 a[100:103], v[64:67], v[28:31], a[100:103]
	v_mfma_f32_16x16x32_f16 a[92:95], v[68:71], v[28:31], a[92:95]
	v_mfma_f32_16x16x32_f16 a[80:83], v[56:59], v[24:27], a[80:83]
	v_mfma_f32_16x16x32_f16 a[76:79], v[60:63], v[24:27], a[76:79]
	v_mfma_f32_16x16x32_f16 a[72:75], v[64:67], v[24:27], a[72:75]
	v_mfma_f32_16x16x32_f16 a[68:71], v[68:71], v[24:27], a[68:71]
	v_mfma_f32_16x16x32_f16 a[64:67], v[56:59], v[16:19], a[64:67]
	v_mfma_f32_16x16x32_f16 a[60:63], v[60:63], v[16:19], a[60:63]
	v_mfma_f32_16x16x32_f16 a[56:59], v[64:67], v[16:19], a[56:59]
	v_mfma_f32_16x16x32_f16 a[52:55], v[68:71], v[16:19], a[52:55]
	v_mfma_f32_16x16x32_f16 a[44:47], v[56:59], v[12:15], a[44:47]
	v_mfma_f32_16x16x32_f16 a[40:43], v[60:63], v[12:15], a[40:43]
	v_mfma_f32_16x16x32_f16 a[36:39], v[64:67], v[12:15], a[36:39]
	v_mfma_f32_16x16x32_f16 a[32:35], v[68:71], v[12:15], a[32:35]
	v_mfma_f32_16x16x32_f16 a[28:31], v[56:59], v[8:11], a[28:31]
	v_mfma_f32_16x16x32_f16 a[24:27], v[60:63], v[8:11], a[24:27]
	v_mfma_f32_16x16x32_f16 a[20:23], v[64:67], v[8:11], a[20:23]
	v_mfma_f32_16x16x32_f16 a[16:19], v[68:71], v[8:11], a[16:19]
	v_mfma_f32_16x16x32_f16 a[12:15], v[56:59], v[4:7], a[12:15]
	v_mfma_f32_16x16x32_f16 a[8:11], v[60:63], v[4:7], a[8:11]
	v_mfma_f32_16x16x32_f16 a[4:7], v[64:67], v[4:7], a[4:7]
	v_mfma_f32_16x16x32_f16 a[0:3], v[68:71], v[4:7], a[0:3]
	s_waitcnt lgkmcnt(3)
	v_mfma_f32_16x16x32_f16 a[252:255], v[0:3], v[44:47], a[252:255]
	s_waitcnt lgkmcnt(2)
	v_mfma_f32_16x16x32_f16 a[248:251], v[20:23], v[44:47], a[248:251]
	s_waitcnt lgkmcnt(1)
	v_mfma_f32_16x16x32_f16 a[244:247], v[36:39], v[44:47], a[244:247]
	s_waitcnt lgkmcnt(0)
	s_barrier
	v_mfma_f32_16x16x32_f16 a[240:243], v[40:43], v[44:47], a[240:243]
	v_mfma_f32_16x16x32_f16 a[236:239], v[0:3], v[32:35], a[236:239]
	v_mfma_f32_16x16x32_f16 a[232:235], v[20:23], v[32:35], a[232:235]
	v_mfma_f32_16x16x32_f16 a[228:231], v[36:39], v[32:35], a[228:231]
	v_mfma_f32_16x16x32_f16 a[224:227], v[40:43], v[32:35], a[224:227]
	v_mfma_f32_16x16x32_f16 a[220:223], v[0:3], v[28:31], a[220:223]
	v_mfma_f32_16x16x32_f16 a[216:219], v[20:23], v[28:31], a[216:219]
	v_mfma_f32_16x16x32_f16 a[212:215], v[36:39], v[28:31], a[212:215]
	v_mfma_f32_16x16x32_f16 a[208:211], v[40:43], v[28:31], a[208:211]
	v_mfma_f32_16x16x32_f16 a[204:207], v[0:3], v[24:27], a[204:207]
	v_mfma_f32_16x16x32_f16 a[200:203], v[20:23], v[24:27], a[200:203]
	v_mfma_f32_16x16x32_f16 a[196:199], v[36:39], v[24:27], a[196:199]
	v_mfma_f32_16x16x32_f16 a[192:195], v[40:43], v[24:27], a[192:195]
	v_mfma_f32_16x16x32_f16 a[188:191], v[0:3], v[16:19], a[188:191]
	v_mfma_f32_16x16x32_f16 a[184:187], v[20:23], v[16:19], a[184:187]
	v_mfma_f32_16x16x32_f16 a[180:183], v[36:39], v[16:19], a[180:183]
	v_mfma_f32_16x16x32_f16 a[176:179], v[40:43], v[16:19], a[176:179]
	v_mfma_f32_16x16x32_f16 a[172:175], v[0:3], v[12:15], a[172:175]
	v_mfma_f32_16x16x32_f16 a[168:171], v[20:23], v[12:15], a[168:171]
	v_mfma_f32_16x16x32_f16 a[164:167], v[36:39], v[12:15], a[164:167]
	v_mfma_f32_16x16x32_f16 a[156:159], v[40:43], v[12:15], a[156:159]
	v_mfma_f32_16x16x32_f16 a[140:143], v[0:3], v[8:11], a[140:143]
	v_mfma_f32_16x16x32_f16 a[132:135], v[20:23], v[8:11], a[132:135]
	v_mfma_f32_16x16x32_f16 a[128:131], v[36:39], v[8:11], a[128:131]
	v_mfma_f32_16x16x32_f16 a[124:127], v[40:43], v[8:11], a[124:127]
	v_mfma_f32_16x16x32_f16 a[96:99], v[0:3], v[4:7], a[96:99]
	v_mfma_f32_16x16x32_f16 a[88:91], v[20:23], v[4:7], a[88:91]
	v_mfma_f32_16x16x32_f16 a[84:87], v[36:39], v[4:7], a[84:87]
	v_mfma_f32_16x16x32_f16 a[48:51], v[40:43], v[4:7], a[48:51]
	s_addk_i32 s17, 0x80
	s_cmp_eq_u32 s17, 0xe1080
	s_cbranch_scc1 .LBB0_952

; #define LD_BF(dst, ks_, nh_) _Pragma("unroll") for (int i = 0; i < 4; ++i) dst[i] = *(const h8*)(sB + ((nh_) * 4 + i) * 16 * G_LD + (ks_) * 32)
; #define MMA_BLK(afx, bfx, nh_) _Pragma("unroll") for (int mi = 0; mi < 8; ++mi) _Pragma("unroll") for (int ni = 0; ni < 4; ++ni) mfma16_acc(acc[mi][(nh_) * 4 + ni], bfx[ni], afx[mi])
; template <class Epi>
; __device__ __forceinline__ void gemm_run(const GemmArgs g, Epi epi, char* smem) {
;     ...
;       LD_BF(bfB, 1, 1);
;       MMA_BLK(afB, bfA, 0);
;       __builtin_amdgcn_sched_barrier(0);
;       MMA_BLK(afB, bfB, 1);
;       __builtin_amdgcn_sched_barrier(0);
;     ...
;       __syncthreads();
;     }
.LBB0_1001:
	ds_read_b128 v[4:7], v92 offset:46144
	ds_read_b128 v[32:35], v92 offset:48448
	ds_read_b128 v[40:43], v92 offset:50752
	ds_read_b128 v[44:47], v92 offset:53056
	s_waitcnt lgkmcnt(7)
	v_mfma_f32_16x16x32_f16 a[204:207], v[56:59], v[36:39], a[204:207]
	s_waitcnt lgkmcnt(6)
	v_mfma_f32_16x16x32_f16 a[200:203], v[60:63], v[36:39], a[200:203]
	s_waitcnt lgkmcnt(5)
	v_mfma_f32_16x16x32_f16 a[196:199], v[64:67], v[36:39], a[196:199]
	s_waitcnt lgkmcnt(4)
	v_mfma_f32_16x16x32_f16 a[188:191], v[68:71], v[36:39], a[188:191]
	v_mfma_f32_16x16x32_f16 a[192:195], v[56:59], v[28:31], a[192:195]
	v_mfma_f32_16x16x32_f16 a[184:187], v[60:63], v[28:31], a[184:187]
	v_mfma_f32_16x16x32_f16 a[180:183], v[64:67], v[28:31], a[180:183]
	v_mfma_f32_16x16x32_f16 a[176:179], v[68:71], v[28:31], a[176:179]
	v_mfma_f32_16x16x32_f16 a[156:159], v[56:59], v[24:27], a[156:159]
	v_mfma_f32_16x16x32_f16 a[152:155], v[60:63], v[24:27], a[152:155]
	v_mfma_f32_16x16x32_f16 a[148:151], v[64:67], v[24:27], a[148:151]
	v_mfma_f32_16x16x32_f16 a[144:147], v[68:71], v[24:27], a[144:147]
	v_mfma_f32_16x16x32_f16 a[124:127], v[56:59], v[20:23], a[124:127]
	v_mfma_f32_16x16x32_f16 a[120:123], v[60:63], v[20:23], a[120:123]
	v_mfma_f32_16x16x32_f16 a[116:119], v[64:67], v[20:23], a[116:119]
	v_mfma_f32_16x16x32_f16 a[112:115], v[68:71], v[20:23], a[112:115]
	v_mfma_f32_16x16x32_f16 a[92:95], v[56:59], v[16:19], a[92:95]
	v_mfma_f32_16x16x32_f16 a[88:91], v[60:63], v[16:19], a[88:91]
	v_mfma_f32_16x16x32_f16 a[84:87], v[64:67], v[16:19], a[84:87]
	v_mfma_f32_16x16x32_f16 a[80:83], v[68:71], v[16:19], a[80:83]
	v_mfma_f32_16x16x32_f16 a[60:63], v[56:59], v[12:15], a[60:63]
	v_mfma_f32_16x16x32_f16 a[56:59], v[60:63], v[12:15], a[56:59]
	v_mfma_f32_16x16x32_f16 a[52:55], v[64:67], v[12:15], a[52:55]
	v_mfma_f32_16x16x32_f16 a[48:51], v[68:71], v[12:15], a[48:51]
	v_mfma_f32_16x16x32_f16 a[32:35], v[56:59], v[8:11], a[32:35]
	v_mfma_f32_16x16x32_f16 a[28:31], v[60:63], v[8:11], a[28:31]
	v_mfma_f32_16x16x32_f16 a[24:27], v[64:67], v[8:11], a[24:27]
	v_mfma_f32_16x16x32_f16 a[20:23], v[68:71], v[8:11], a[20:23]
	v_mfma_f32_16x16x32_f16 a[12:15], v[56:59], v[0:3], a[12:15]
	v_mfma_f32_16x16x32_f16 a[8:11], v[60:63], v[0:3], a[8:11]
	v_mfma_f32_16x16x32_f16 a[4:7], v[64:67], v[0:3], a[4:7]
	v_mfma_f32_16x16x32_f16 a[0:3], v[68:71], v[0:3], a[0:3]
	s_waitcnt lgkmcnt(3)
	v_mfma_f32_16x16x32_f16 a[240:243], v[4:7], v[36:39], a[240:243]
	s_waitcnt lgkmcnt(2)
	v_mfma_f32_16x16x32_f16 a[252:255], v[32:35], v[36:39], a[252:255]
	s_waitcnt lgkmcnt(1)
	v_mfma_f32_16x16x32_f16 a[248:251], v[40:43], v[36:39], a[248:251]
	s_waitcnt lgkmcnt(0)
	s_barrier
	v_mfma_f32_16x16x32_f16 a[244:247], v[44:47], v[36:39], a[244:247]
	v_mfma_f32_16x16x32_f16 a[236:239], v[4:7], v[28:31], a[236:239]
	v_mfma_f32_16x16x32_f16 a[232:235], v[32:35], v[28:31], a[232:235]
	v_mfma_f32_16x16x32_f16 a[228:231], v[40:43], v[28:31], a[228:231]
	v_mfma_f32_16x16x32_f16 a[224:227], v[44:47], v[28:31], a[224:227]
	v_mfma_f32_16x16x32_f16 a[220:223], v[4:7], v[24:27], a[220:223]
	v_mfma_f32_16x16x32_f16 a[216:219], v[32:35], v[24:27], a[216:219]
	v_mfma_f32_16x16x32_f16 a[212:215], v[40:43], v[24:27], a[212:215]
	v_mfma_f32_16x16x32_f16 a[208:211], v[44:47], v[24:27], a[208:211]
	v_mfma_f32_16x16x32_f16 a[172:175], v[4:7], v[20:23], a[172:175]
	v_mfma_f32_16x16x32_f16 a[168:171], v[32:35], v[20:23], a[168:171]
	v_mfma_f32_16x16x32_f16 a[164:167], v[40:43], v[20:23], a[164:167]
	v_mfma_f32_16x16x32_f16 a[160:163], v[44:47], v[20:23], a[160:163]
	v_mfma_f32_16x16x32_f16 a[140:143], v[4:7], v[16:19], a[140:143]
	v_mfma_f32_16x16x32_f16 a[136:139], v[32:35], v[16:19], a[136:139]
	v_mfma_f32_16x16x32_f16 a[132:135], v[40:43], v[16:19], a[132:135]
	v_mfma_f32_16x16x32_f16 a[128:131], v[44:47], v[16:19], a[128:131]
	v_mfma_f32_16x16x32_f16 a[108:111], v[4:7], v[12:15], a[108:111]
	v_mfma_f32_16x16x32_f16 a[104:107], v[32:35], v[12:15], a[104:107]
	v_mfma_f32_16x16x32_f16 a[100:103], v[40:43], v[12:15], a[100:103]
	v_mfma_f32_16x16x32_f16 a[96:99], v[44:47], v[12:15], a[96:99]
	v_mfma_f32_16x16x32_f16 a[76:79], v[4:7], v[8:11], a[76:79]
	v_mfma_f32_16x16x32_f16 a[72:75], v[32:35], v[8:11], a[72:75]
	v_mfma_f32_16x16x32_f16 a[68:71], v[40:43], v[8:11], a[68:71]
	v_mfma_f32_16x16x32_f16 a[64:67], v[44:47], v[8:11], a[64:67]
	v_mfma_f32_16x16x32_f16 a[44:47], v[4:7], v[0:3], a[44:47]
	v_mfma_f32_16x16x32_f16 a[40:43], v[32:35], v[0:3], a[40:43]
	v_mfma_f32_16x16x32_f16 a[36:39], v[40:43], v[0:3], a[36:39]
	v_mfma_f32_16x16x32_f16 a[16:19], v[44:47], v[0:3], a[16:19]
	s_addk_i32 s84, 0x80
	s_cmp_eq_u32 s84, 0x26ac80
	s_cbranch_scc1 .LBB0_999

; #define LD_BF(dst, ks_, nh_) _Pragma("unroll") for (int i = 0; i < 4; ++i) dst[i] = *(const h8*)(sB + ((nh_) * 4 + i) * 16 * G_LD + (ks_) * 32)
; #define MMA_BLK(afx, bfx, nh_) _Pragma("unroll") for (int mi = 0; mi < 8; ++mi) _Pragma("unroll") for (int ni = 0; ni < 4; ++ni) mfma16_acc(acc[mi][(nh_) * 4 + ni], bfx[ni], afx[mi])
; template <class Epi>
; __device__ __forceinline__ void gemm_run(const GemmArgs g, Epi epi, char* smem) {
;     ...
;       LD_BF(bfB, 1, 1);
;       MMA_BLK(afB, bfA, 0);
;       __builtin_amdgcn_sched_barrier(0);
;       MMA_BLK(afB, bfB, 1);
;       __builtin_amdgcn_sched_barrier(0);
;     ...
;       __syncthreads();
;     }
.LBB0_1007:
	ds_read_b128 v[4:7], v106 offset:46144
	ds_read_b128 v[32:35], v106 offset:48448
	ds_read_b128 v[40:43], v106 offset:50752
	ds_read_b128 v[44:47], v106 offset:53056
	s_waitcnt lgkmcnt(7)
	v_mfma_f32_16x16x32_f16 a[116:119], v[56:59], v[36:39], a[116:119]
	s_waitcnt lgkmcnt(6)
	v_mfma_f32_16x16x32_f16 a[108:111], v[60:63], v[36:39], a[108:111]
	s_waitcnt lgkmcnt(5)
	v_mfma_f32_16x16x32_f16 a[100:103], v[64:67], v[36:39], a[100:103]
	s_waitcnt lgkmcnt(4)
	v_mfma_f32_16x16x32_f16 a[160:163], v[68:71], v[36:39], a[160:163]
	v_mfma_f32_16x16x32_f16 a[152:155], v[56:59], v[28:31], a[152:155]
	v_mfma_f32_16x16x32_f16 a[148:151], v[60:63], v[28:31], a[148:151]
	v_mfma_f32_16x16x32_f16 a[144:147], v[64:67], v[28:31], a[144:147]
	v_mfma_f32_16x16x32_f16 a[136:139], v[68:71], v[28:31], a[136:139]
	v_mfma_f32_16x16x32_f16 a[120:123], v[56:59], v[24:27], a[120:123]
	v_mfma_f32_16x16x32_f16 a[112:115], v[60:63], v[24:27], a[112:115]
	v_mfma_f32_16x16x32_f16 a[104:107], v[64:67], v[24:27], a[104:107]
	v_mfma_f32_16x16x32_f16 a[92:95], v[68:71], v[24:27], a[92:95]
	v_mfma_f32_16x16x32_f16 a[80:83], v[56:59], v[20:23], a[80:83]
	v_mfma_f32_16x16x32_f16 a[76:79], v[60:63], v[20:23], a[76:79]
	v_mfma_f32_16x16x32_f16 a[72:75], v[64:67], v[20:23], a[72:75]
	v_mfma_f32_16x16x32_f16 a[68:71], v[68:71], v[20:23], a[68:71]
	v_mfma_f32_16x16x32_f16 a[64:67], v[56:59], v[16:19], a[64:67]
	v_mfma_f32_16x16x32_f16 a[60:63], v[60:63], v[16:19], a[60:63]
	v_mfma_f32_16x16x32_f16 a[56:59], v[64:67], v[16:19], a[56:59]
	v_mfma_f32_16x16x32_f16 a[52:55], v[68:71], v[16:19], a[52:55]
	v_mfma_f32_16x16x32_f16 a[44:47], v[56:59], v[12:15], a[44:47]
	v_mfma_f32_16x16x32_f16 a[40:43], v[60:63], v[12:15], a[40:43]
	v_mfma_f32_16x16x32_f16 a[36:39], v[64:67], v[12:15], a[36:39]
	v_mfma_f32_16x16x32_f16 a[32:35], v[68:71], v[12:15], a[32:35]
	v_mfma_f32_16x16x32_f16 a[28:31], v[56:59], v[8:11], a[28:31]
	v_mfma_f32_16x16x32_f16 a[24:27], v[60:63], v[8:11], a[24:27]
	v_mfma_f32_16x16x32_f16 a[20:23], v[64:67], v[8:11], a[20:23]
	v_mfma_f32_16x16x32_f16 a[16:19], v[68:71], v[8:11], a[16:19]
	v_mfma_f32_16x16x32_f16 a[12:15], v[56:59], v[0:3], a[12:15]
	v_mfma_f32_16x16x32_f16 a[8:11], v[60:63], v[0:3], a[8:11]
	v_mfma_f32_16x16x32_f16 a[4:7], v[64:67], v[0:3], a[4:7]
	v_mfma_f32_16x16x32_f16 a[0:3], v[68:71], v[0:3], a[0:3]
	s_waitcnt lgkmcnt(3)
	v_mfma_f32_16x16x32_f16 a[252:255], v[4:7], v[36:39], a[252:255]
	s_waitcnt lgkmcnt(2)
	v_mfma_f32_16x16x32_f16 a[248:251], v[32:35], v[36:39], a[248:251]
	s_waitcnt lgkmcnt(1)
	v_mfma_f32_16x16x32_f16 a[244:247], v[40:43], v[36:39], a[244:247]
	s_waitcnt lgkmcnt(0)
	s_barrier
	v_mfma_f32_16x16x32_f16 a[240:243], v[44:47], v[36:39], a[240:243]
	v_mfma_f32_16x16x32_f16 a[236:239], v[4:7], v[28:31], a[236:239]
	v_mfma_f32_16x16x32_f16 a[232:235], v[32:35], v[28:31], a[232:235]
	v_mfma_f32_16x16x32_f16 a[228:231], v[40:43], v[28:31], a[228:231]
	v_mfma_f32_16x16x32_f16 a[224:227], v[44:47], v[28:31], a[224:227]
	v_mfma_f32_16x16x32_f16 a[220:223], v[4:7], v[24:27], a[220:223]
	v_mfma_f32_16x16x32_f16 a[216:219], v[32:35], v[24:27], a[216:219]
	v_mfma_f32_16x16x32_f16 a[212:215], v[40:43], v[24:27], a[212:215]
	v_mfma_f32_16x16x32_f16 a[208:211], v[44:47], v[24:27], a[208:211]
	v_mfma_f32_16x16x32_f16 a[204:207], v[4:7], v[20:23], a[204:207]
	v_mfma_f32_16x16x32_f16 a[200:203], v[32:35], v[20:23], a[200:203]
	v_mfma_f32_16x16x32_f16 a[196:199], v[40:43], v[20:23], a[196:199]
	v_mfma_f32_16x16x32_f16 a[192:195], v[44:47], v[20:23], a[192:195]
	v_mfma_f32_16x16x32_f16 a[188:191], v[4:7], v[16:19], a[188:191]
	v_mfma_f32_16x16x32_f16 a[184:187], v[32:35], v[16:19], a[184:187]
	v_mfma_f32_16x16x32_f16 a[180:183], v[40:43], v[16:19], a[180:183]
	v_mfma_f32_16x16x32_f16 a[176:179], v[44:47], v[16:19], a[176:179]
	v_mfma_f32_16x16x32_f16 a[172:175], v[4:7], v[12:15], a[172:175]
	v_mfma_f32_16x16x32_f16 a[168:171], v[32:35], v[12:15], a[168:171]
	v_mfma_f32_16x16x32_f16 a[164:167], v[40:43], v[12:15], a[164:167]
	v_mfma_f32_16x16x32_f16 a[156:159], v[44:47], v[12:15], a[156:159]
	v_mfma_f32_16x16x32_f16 a[140:143], v[4:7], v[8:11], a[140:143]
	v_mfma_f32_16x16x32_f16 a[132:135], v[32:35], v[8:11], a[132:135]
	v_mfma_f32_16x16x32_f16 a[128:131], v[40:43], v[8:11], a[128:131]
	v_mfma_f32_16x16x32_f16 a[124:127], v[44:47], v[8:11], a[124:127]
	v_mfma_f32_16x16x32_f16 a[96:99], v[4:7], v[0:3], a[96:99]
	v_mfma_f32_16x16x32_f16 a[88:91], v[32:35], v[0:3], a[88:91]
	v_mfma_f32_16x16x32_f16 a[84:87], v[40:43], v[0:3], a[84:87]
	v_mfma_f32_16x16x32_f16 a[48:51], v[44:47], v[0:3], a[48:51]
	s_addk_i32 s7, 0x80
	s_cmp_eq_u32 s7, 0xe1080
	s_cbranch_scc1 .LBB0_1010

; #define LD_BF(dst, ks_, nh_) _Pragma("unroll") for (int i = 0; i < 4; ++i) dst[i] = *(const h8*)(sB + ((nh_) * 4 + i) * 16 * G_LD + (ks_) * 32)
; #define MMA_BLK(afx, bfx, nh_) _Pragma("unroll") for (int mi = 0; mi < 8; ++mi) _Pragma("unroll") for (int ni = 0; ni < 4; ++ni) mfma16_acc(acc[mi][(nh_) * 4 + ni], bfx[ni], afx[mi])
; template <class Epi>
; __device__ __forceinline__ void gemm_run(const GemmArgs g, Epi epi, char* smem) {
;     ...
;       LD_BF(bfB, 1, 1);
;       MMA_BLK(afB, bfA, 0);
;       __builtin_amdgcn_sched_barrier(0);
;       MMA_BLK(afB, bfB, 1);
;       __builtin_amdgcn_sched_barrier(0);
;     ...
;       __syncthreads();
;     }
.LBB0_1200:
	ds_read_b128 v[4:7], v92 offset:46144
	ds_read_b128 v[32:35], v92 offset:48448
	ds_read_b128 v[40:43], v92 offset:50752
	ds_read_b128 v[44:47], v92 offset:53056
	s_waitcnt lgkmcnt(7)
	v_mfma_f32_16x16x32_f16 a[252:255], v[56:59], v[36:39], a[252:255]
	s_waitcnt lgkmcnt(6)
	v_mfma_f32_16x16x32_f16 a[244:247], v[60:63], v[36:39], a[244:247]
	s_waitcnt lgkmcnt(5)
	v_mfma_f32_16x16x32_f16 a[236:239], v[64:67], v[36:39], a[236:239]
	s_waitcnt lgkmcnt(4)
	v_mfma_f32_16x16x32_f16 a[228:231], v[68:71], v[36:39], a[228:231]
	v_mfma_f32_16x16x32_f16 a[220:223], v[56:59], v[28:31], a[220:223]
	v_mfma_f32_16x16x32_f16 a[212:215], v[60:63], v[28:31], a[212:215]
	v_mfma_f32_16x16x32_f16 a[204:207], v[64:67], v[28:31], a[204:207]
	v_mfma_f32_16x16x32_f16 a[196:199], v[68:71], v[28:31], a[196:199]
	v_mfma_f32_16x16x32_f16 a[188:191], v[56:59], v[24:27], a[188:191]
	v_mfma_f32_16x16x32_f16 a[180:183], v[60:63], v[24:27], a[180:183]
	v_mfma_f32_16x16x32_f16 a[172:175], v[64:67], v[24:27], a[172:175]
	v_mfma_f32_16x16x32_f16 a[164:167], v[68:71], v[24:27], a[164:167]
	v_mfma_f32_16x16x32_f16 a[156:159], v[56:59], v[20:23], a[156:159]
	v_mfma_f32_16x16x32_f16 a[148:151], v[60:63], v[20:23], a[148:151]
	v_mfma_f32_16x16x32_f16 a[140:143], v[64:67], v[20:23], a[140:143]
	v_mfma_f32_16x16x32_f16 a[132:135], v[68:71], v[20:23], a[132:135]
	v_mfma_f32_16x16x32_f16 a[124:127], v[56:59], v[16:19], a[124:127]
	v_mfma_f32_16x16x32_f16 a[116:119], v[60:63], v[16:19], a[116:119]
	v_mfma_f32_16x16x32_f16 a[108:111], v[64:67], v[16:19], a[108:111]
	v_mfma_f32_16x16x32_f16 a[100:103], v[68:71], v[16:19], a[100:103]
	v_mfma_f32_16x16x32_f16 a[92:95], v[56:59], v[12:15], a[92:95]
	v_mfma_f32_16x16x32_f16 a[84:87], v[60:63], v[12:15], a[84:87]
	v_mfma_f32_16x16x32_f16 a[76:79], v[64:67], v[12:15], a[76:79]
	v_mfma_f32_16x16x32_f16 a[68:71], v[68:71], v[12:15], a[68:71]
	v_mfma_f32_16x16x32_f16 a[60:63], v[56:59], v[8:11], a[60:63]
	v_mfma_f32_16x16x32_f16 a[52:55], v[60:63], v[8:11], a[52:55]
	v_mfma_f32_16x16x32_f16 a[44:47], v[64:67], v[8:11], a[44:47]
	v_mfma_f32_16x16x32_f16 a[36:39], v[68:71], v[8:11], a[36:39]
	v_mfma_f32_16x16x32_f16 a[28:31], v[56:59], v[0:3], a[28:31]
	v_mfma_f32_16x16x32_f16 a[24:27], v[60:63], v[0:3], a[24:27]
	v_mfma_f32_16x16x32_f16 a[20:23], v[64:67], v[0:3], a[20:23]
	v_mfma_f32_16x16x32_f16 a[12:15], v[68:71], v[0:3], a[12:15]
	s_waitcnt lgkmcnt(3)
	v_mfma_f32_16x16x32_f16 a[248:251], v[4:7], v[36:39], a[248:251]
	s_waitcnt lgkmcnt(2)
	v_mfma_f32_16x16x32_f16 a[240:243], v[32:35], v[36:39], a[240:243]
	s_waitcnt lgkmcnt(1)
	v_mfma_f32_16x16x32_f16 a[232:235], v[40:43], v[36:39], a[232:235]
	s_waitcnt lgkmcnt(0)
	s_barrier
	v_mfma_f32_16x16x32_f16 a[224:227], v[44:47], v[36:39], a[224:227]
	v_mfma_f32_16x16x32_f16 a[216:219], v[4:7], v[28:31], a[216:219]
	v_mfma_f32_16x16x32_f16 a[208:211], v[32:35], v[28:31], a[208:211]
	v_mfma_f32_16x16x32_f16 a[200:203], v[40:43], v[28:31], a[200:203]
	v_mfma_f32_16x16x32_f16 a[192:195], v[44:47], v[28:31], a[192:195]
	v_mfma_f32_16x16x32_f16 a[184:187], v[4:7], v[24:27], a[184:187]
	v_mfma_f32_16x16x32_f16 a[176:179], v[32:35], v[24:27], a[176:179]
	v_mfma_f32_16x16x32_f16 a[168:171], v[40:43], v[24:27], a[168:171]
	v_mfma_f32_16x16x32_f16 a[160:163], v[44:47], v[24:27], a[160:163]
	v_mfma_f32_16x16x32_f16 a[152:155], v[4:7], v[20:23], a[152:155]
	v_mfma_f32_16x16x32_f16 a[144:147], v[32:35], v[20:23], a[144:147]
	v_mfma_f32_16x16x32_f16 a[136:139], v[40:43], v[20:23], a[136:139]
	v_mfma_f32_16x16x32_f16 a[128:131], v[44:47], v[20:23], a[128:131]
	v_mfma_f32_16x16x32_f16 a[120:123], v[4:7], v[16:19], a[120:123]
	v_mfma_f32_16x16x32_f16 a[112:115], v[32:35], v[16:19], a[112:115]
	v_mfma_f32_16x16x32_f16 a[104:107], v[40:43], v[16:19], a[104:107]
	v_mfma_f32_16x16x32_f16 a[96:99], v[44:47], v[16:19], a[96:99]
	v_mfma_f32_16x16x32_f16 a[88:91], v[4:7], v[12:15], a[88:91]
	v_mfma_f32_16x16x32_f16 a[80:83], v[32:35], v[12:15], a[80:83]
	v_mfma_f32_16x16x32_f16 a[72:75], v[40:43], v[12:15], a[72:75]
	v_mfma_f32_16x16x32_f16 a[64:67], v[44:47], v[12:15], a[64:67]
	v_mfma_f32_16x16x32_f16 a[56:59], v[4:7], v[8:11], a[56:59]
	v_mfma_f32_16x16x32_f16 a[48:51], v[32:35], v[8:11], a[48:51]
	v_mfma_f32_16x16x32_f16 a[40:43], v[40:43], v[8:11], a[40:43]
	v_mfma_f32_16x16x32_f16 a[32:35], v[44:47], v[8:11], a[32:35]
	v_mfma_f32_16x16x32_f16 a[16:19], v[4:7], v[0:3], a[16:19]
	v_mfma_f32_16x16x32_f16 a[8:11], v[32:35], v[0:3], a[8:11]
	v_mfma_f32_16x16x32_f16 a[4:7], v[40:43], v[0:3], a[4:7]
	v_mfma_f32_16x16x32_f16 a[0:3], v[44:47], v[0:3], a[0:3]
	s_addk_i32 s3, 0x80
	s_cmp_eq_u32 s3, 0xe1080
	s_cbranch_scc1 .LBB0_1203

; #define LD_BF(dst, ks_, nh_) _Pragma("unroll") for (int i = 0; i < 4; ++i) dst[i] = *(const h8*)(sB + ((nh_) * 4 + i) * 16 * G_LD + (ks_) * 32)
; #define MMA_BLK(afx, bfx, nh_) _Pragma("unroll") for (int mi = 0; mi < 8; ++mi) _Pragma("unroll") for (int ni = 0; ni < 4; ++ni) mfma16_acc(acc[mi][(nh_) * 4 + ni], bfx[ni], afx[mi])
; template <class Epi>
; __device__ __forceinline__ void gemm_run(const GemmArgs g, Epi epi, char* smem) {
;     ...
;       LD_BF(bfB, 1, 1);
;       MMA_BLK(afB, bfA, 0);
;       __builtin_amdgcn_sched_barrier(0);
;       MMA_BLK(afB, bfB, 1);
;       __builtin_amdgcn_sched_barrier(0);
;     ...
;       __syncthreads();
;     }
.LBB0_1622:
	ds_read_b128 v[0:3], v104 offset:46144
	ds_read_b128 v[4:7], v104 offset:48448
	ds_read_b128 v[8:11], v104 offset:50752
	ds_read_b128 v[12:15], v104 offset:53056
	s_waitcnt lgkmcnt(7)
	v_mfma_f32_16x16x32_f16 a[140:143], v[64:67], v[60:63], a[140:143]
	s_waitcnt lgkmcnt(6)
	v_mfma_f32_16x16x32_f16 a[136:139], v[68:71], v[60:63], a[136:139]
	s_waitcnt lgkmcnt(5)
	v_mfma_f32_16x16x32_f16 a[128:131], v[72:75], v[60:63], a[128:131]
	s_waitcnt lgkmcnt(4)
	v_mfma_f32_16x16x32_f16 a[120:123], v[76:79], v[60:63], a[120:123]
	v_mfma_f32_16x16x32_f16 a[156:159], v[64:67], v[52:55], a[156:159]
	v_mfma_f32_16x16x32_f16 a[152:155], v[68:71], v[52:55], a[152:155]
	v_mfma_f32_16x16x32_f16 a[148:151], v[72:75], v[52:55], a[148:151]
	v_mfma_f32_16x16x32_f16 a[144:147], v[76:79], v[52:55], a[144:147]
	v_mfma_f32_16x16x32_f16 a[108:111], v[64:67], v[48:51], a[108:111]
	v_mfma_f32_16x16x32_f16 a[104:107], v[68:71], v[48:51], a[104:107]
	v_mfma_f32_16x16x32_f16 a[100:103], v[72:75], v[48:51], a[100:103]
	v_mfma_f32_16x16x32_f16 a[96:99], v[76:79], v[48:51], a[96:99]
	v_mfma_f32_16x16x32_f16 a[76:79], v[64:67], v[40:43], a[76:79]
	v_mfma_f32_16x16x32_f16 a[72:75], v[68:71], v[40:43], a[72:75]
	v_mfma_f32_16x16x32_f16 a[68:71], v[72:75], v[40:43], a[68:71]
	v_mfma_f32_16x16x32_f16 a[64:67], v[76:79], v[40:43], a[64:67]
	v_mfma_f32_16x16x32_f16 a[60:63], v[64:67], v[36:39], a[60:63]
	v_mfma_f32_16x16x32_f16 a[56:59], v[68:71], v[36:39], a[56:59]
	v_mfma_f32_16x16x32_f16 a[52:55], v[72:75], v[36:39], a[52:55]
	v_mfma_f32_16x16x32_f16 a[48:51], v[76:79], v[36:39], a[48:51]
	v_mfma_f32_16x16x32_f16 a[44:47], v[64:67], v[32:35], a[44:47]
	v_mfma_f32_16x16x32_f16 a[40:43], v[68:71], v[32:35], a[40:43]
	v_mfma_f32_16x16x32_f16 a[36:39], v[72:75], v[32:35], a[36:39]
	v_mfma_f32_16x16x32_f16 a[32:35], v[76:79], v[32:35], a[32:35]
	v_mfma_f32_16x16x32_f16 a[28:31], v[64:67], v[24:27], a[28:31]
	v_mfma_f32_16x16x32_f16 a[24:27], v[68:71], v[24:27], a[24:27]
	v_mfma_f32_16x16x32_f16 a[20:23], v[72:75], v[24:27], a[20:23]
	v_mfma_f32_16x16x32_f16 a[16:19], v[76:79], v[24:27], a[16:19]
	v_mfma_f32_16x16x32_f16 a[12:15], v[64:67], v[16:19], a[12:15]
	v_mfma_f32_16x16x32_f16 a[8:11], v[68:71], v[16:19], a[8:11]
	v_mfma_f32_16x16x32_f16 a[4:7], v[72:75], v[16:19], a[4:7]
	v_mfma_f32_16x16x32_f16 a[0:3], v[76:79], v[16:19], a[0:3]
	s_waitcnt lgkmcnt(3)
	v_mfma_f32_16x16x32_f16 a[252:255], v[0:3], v[60:63], a[252:255]
	s_waitcnt lgkmcnt(2)
	v_mfma_f32_16x16x32_f16 a[248:251], v[4:7], v[60:63], a[248:251]
	s_waitcnt lgkmcnt(1)
	v_mfma_f32_16x16x32_f16 a[244:247], v[8:11], v[60:63], a[244:247]
	s_waitcnt lgkmcnt(0)
	s_barrier
	v_mfma_f32_16x16x32_f16 a[240:243], v[12:15], v[60:63], a[240:243]
	v_mfma_f32_16x16x32_f16 a[236:239], v[0:3], v[52:55], a[236:239]
	v_mfma_f32_16x16x32_f16 a[232:235], v[4:7], v[52:55], a[232:235]
	v_mfma_f32_16x16x32_f16 a[228:231], v[8:11], v[52:55], a[228:231]
	v_mfma_f32_16x16x32_f16 a[224:227], v[12:15], v[52:55], a[224:227]
	v_mfma_f32_16x16x32_f16 a[220:223], v[0:3], v[48:51], a[220:223]
	v_mfma_f32_16x16x32_f16 a[216:219], v[4:7], v[48:51], a[216:219]
	v_mfma_f32_16x16x32_f16 a[212:215], v[8:11], v[48:51], a[212:215]
	v_mfma_f32_16x16x32_f16 a[208:211], v[12:15], v[48:51], a[208:211]
	v_mfma_f32_16x16x32_f16 a[204:207], v[0:3], v[40:43], a[204:207]
	v_mfma_f32_16x16x32_f16 a[200:203], v[4:7], v[40:43], a[200:203]
	v_mfma_f32_16x16x32_f16 a[196:199], v[8:11], v[40:43], a[196:199]
	v_mfma_f32_16x16x32_f16 a[192:195], v[12:15], v[40:43], a[192:195]
	v_mfma_f32_16x16x32_f16 a[188:191], v[0:3], v[36:39], a[188:191]
	v_mfma_f32_16x16x32_f16 a[184:187], v[4:7], v[36:39], a[184:187]
	v_mfma_f32_16x16x32_f16 a[180:183], v[8:11], v[36:39], a[180:183]
	v_mfma_f32_16x16x32_f16 a[176:179], v[12:15], v[36:39], a[176:179]
	v_mfma_f32_16x16x32_f16 a[172:175], v[0:3], v[32:35], a[172:175]
	v_mfma_f32_16x16x32_f16 a[168:171], v[4:7], v[32:35], a[168:171]
	v_mfma_f32_16x16x32_f16 a[164:167], v[8:11], v[32:35], a[164:167]
	v_mfma_f32_16x16x32_f16 a[160:163], v[12:15], v[32:35], a[160:163]
	v_mfma_f32_16x16x32_f16 a[132:135], v[0:3], v[24:27], a[132:135]
	v_mfma_f32_16x16x32_f16 a[124:127], v[4:7], v[24:27], a[124:127]
	v_mfma_f32_16x16x32_f16 a[116:119], v[8:11], v[24:27], a[116:119]
	v_mfma_f32_16x16x32_f16 a[112:115], v[12:15], v[24:27], a[112:115]
	v_mfma_f32_16x16x32_f16 a[92:95], v[0:3], v[16:19], a[92:95]
	v_mfma_f32_16x16x32_f16 a[88:91], v[4:7], v[16:19], a[88:91]
	v_mfma_f32_16x16x32_f16 a[84:87], v[8:11], v[16:19], a[84:87]
	v_mfma_f32_16x16x32_f16 a[80:83], v[12:15], v[16:19], a[80:83]
	s_addk_i32 s19, 0x80
	s_cmp_eq_u32 s19, 0x38480
	s_cbranch_scc1 .LBB0_1620

; #define LD_BF(dst, ks_, nh_) _Pragma("unroll") for (int i = 0; i < 4; ++i) dst[i] = *(const h8*)(sB + ((nh_) * 4 + i) * 16 * G_LD + (ks_) * 32)
; #define MMA_BLK(afx, bfx, nh_) _Pragma("unroll") for (int mi = 0; mi < 8; ++mi) _Pragma("unroll") for (int ni = 0; ni < 4; ++ni) mfma16_acc(acc[mi][(nh_) * 4 + ni], bfx[ni], afx[mi])
; template <class Epi>
; __device__ __forceinline__ void gemm_run(const GemmArgs g, Epi epi, char* smem) {
;     ...
;       LD_BF(bfB, 1, 1);
;       MMA_BLK(afB, bfA, 0);
;       __builtin_amdgcn_sched_barrier(0);
;       MMA_BLK(afB, bfB, 1);
;       __builtin_amdgcn_sched_barrier(0);
;     ...
;       __syncthreads();
;     }
.LBB0_1630:
	ds_read_b128 v[0:3], v104 offset:46144
	ds_read_b128 v[4:7], v104 offset:48448
	ds_read_b128 v[8:11], v104 offset:50752
	ds_read_b128 v[12:15], v104 offset:53056
	s_waitcnt lgkmcnt(7)
	v_mfma_f32_16x16x32_f16 a[252:255], v[64:67], v[60:63], a[252:255]
	s_waitcnt lgkmcnt(6)
	v_mfma_f32_16x16x32_f16 a[236:239], v[68:71], v[60:63], a[236:239]
	s_waitcnt lgkmcnt(5)
	v_mfma_f32_16x16x32_f16 a[228:231], v[72:75], v[60:63], a[228:231]
	s_waitcnt lgkmcnt(4)
	v_mfma_f32_16x16x32_f16 a[224:227], v[76:79], v[60:63], a[224:227]
	v_mfma_f32_16x16x32_f16 a[212:215], v[64:67], v[52:55], a[212:215]
	v_mfma_f32_16x16x32_f16 a[204:207], v[68:71], v[52:55], a[204:207]
	v_mfma_f32_16x16x32_f16 a[196:199], v[72:75], v[52:55], a[196:199]
	v_mfma_f32_16x16x32_f16 a[192:195], v[76:79], v[52:55], a[192:195]
	v_mfma_f32_16x16x32_f16 a[180:183], v[64:67], v[48:51], a[180:183]
	v_mfma_f32_16x16x32_f16 a[172:175], v[68:71], v[48:51], a[172:175]
	v_mfma_f32_16x16x32_f16 a[164:167], v[72:75], v[48:51], a[164:167]
	v_mfma_f32_16x16x32_f16 a[160:163], v[76:79], v[48:51], a[160:163]
	v_mfma_f32_16x16x32_f16 a[148:151], v[64:67], v[40:43], a[148:151]
	v_mfma_f32_16x16x32_f16 a[140:143], v[68:71], v[40:43], a[140:143]
	v_mfma_f32_16x16x32_f16 a[132:135], v[72:75], v[40:43], a[132:135]
	v_mfma_f32_16x16x32_f16 a[128:131], v[76:79], v[40:43], a[128:131]
	v_mfma_f32_16x16x32_f16 a[116:119], v[64:67], v[36:39], a[116:119]
	v_mfma_f32_16x16x32_f16 a[108:111], v[68:71], v[36:39], a[108:111]
	v_mfma_f32_16x16x32_f16 a[100:103], v[72:75], v[36:39], a[100:103]
	v_mfma_f32_16x16x32_f16 a[96:99], v[76:79], v[36:39], a[96:99]
	v_mfma_f32_16x16x32_f16 a[84:87], v[64:67], v[32:35], a[84:87]
	v_mfma_f32_16x16x32_f16 a[76:79], v[68:71], v[32:35], a[76:79]
	v_mfma_f32_16x16x32_f16 a[68:71], v[72:75], v[32:35], a[68:71]
	v_mfma_f32_16x16x32_f16 a[64:67], v[76:79], v[32:35], a[64:67]
	v_mfma_f32_16x16x32_f16 a[52:55], v[64:67], v[24:27], a[52:55]
	v_mfma_f32_16x16x32_f16 a[44:47], v[68:71], v[24:27], a[44:47]
	v_mfma_f32_16x16x32_f16 a[36:39], v[72:75], v[24:27], a[36:39]
	v_mfma_f32_16x16x32_f16 a[32:35], v[76:79], v[24:27], a[32:35]
	v_mfma_f32_16x16x32_f16 a[24:27], v[64:67], v[16:19], a[24:27]
	v_mfma_f32_16x16x32_f16 a[16:19], v[68:71], v[16:19], a[16:19]
	v_mfma_f32_16x16x32_f16 a[8:11], v[72:75], v[16:19], a[8:11]
	v_mfma_f32_16x16x32_f16 a[0:3], v[76:79], v[16:19], a[0:3]
	s_waitcnt lgkmcnt(3)
	v_mfma_f32_16x16x32_f16 a[248:251], v[0:3], v[60:63], a[248:251]
	s_waitcnt lgkmcnt(2)
	v_mfma_f32_16x16x32_f16 a[244:247], v[4:7], v[60:63], a[244:247]
	s_waitcnt lgkmcnt(1)
	v_mfma_f32_16x16x32_f16 a[240:243], v[8:11], v[60:63], a[240:243]
	s_waitcnt lgkmcnt(0)
	s_barrier
	v_mfma_f32_16x16x32_f16 a[232:235], v[12:15], v[60:63], a[232:235]
	v_mfma_f32_16x16x32_f16 a[220:223], v[0:3], v[52:55], a[220:223]
	v_mfma_f32_16x16x32_f16 a[216:219], v[4:7], v[52:55], a[216:219]
	v_mfma_f32_16x16x32_f16 a[208:211], v[8:11], v[52:55], a[208:211]
	v_mfma_f32_16x16x32_f16 a[200:203], v[12:15], v[52:55], a[200:203]
	v_mfma_f32_16x16x32_f16 a[188:191], v[0:3], v[48:51], a[188:191]
	v_mfma_f32_16x16x32_f16 a[184:187], v[4:7], v[48:51], a[184:187]
	v_mfma_f32_16x16x32_f16 a[176:179], v[8:11], v[48:51], a[176:179]
	v_mfma_f32_16x16x32_f16 a[168:171], v[12:15], v[48:51], a[168:171]
	v_mfma_f32_16x16x32_f16 a[156:159], v[0:3], v[40:43], a[156:159]
	v_mfma_f32_16x16x32_f16 a[152:155], v[4:7], v[40:43], a[152:155]
	v_mfma_f32_16x16x32_f16 a[144:147], v[8:11], v[40:43], a[144:147]
	v_mfma_f32_16x16x32_f16 a[136:139], v[12:15], v[40:43], a[136:139]
	v_mfma_f32_16x16x32_f16 a[124:127], v[0:3], v[36:39], a[124:127]
	v_mfma_f32_16x16x32_f16 a[120:123], v[4:7], v[36:39], a[120:123]
	v_mfma_f32_16x16x32_f16 a[112:115], v[8:11], v[36:39], a[112:115]
	v_mfma_f32_16x16x32_f16 a[104:107], v[12:15], v[36:39], a[104:107]
	v_mfma_f32_16x16x32_f16 a[92:95], v[0:3], v[32:35], a[92:95]
	v_mfma_f32_16x16x32_f16 a[88:91], v[4:7], v[32:35], a[88:91]
	v_mfma_f32_16x16x32_f16 a[80:83], v[8:11], v[32:35], a[80:83]
	v_mfma_f32_16x16x32_f16 a[72:75], v[12:15], v[32:35], a[72:75]
	v_mfma_f32_16x16x32_f16 a[60:63], v[0:3], v[24:27], a[60:63]
	v_mfma_f32_16x16x32_f16 a[56:59], v[4:7], v[24:27], a[56:59]
	v_mfma_f32_16x16x32_f16 a[48:51], v[8:11], v[24:27], a[48:51]
	v_mfma_f32_16x16x32_f16 a[40:43], v[12:15], v[24:27], a[40:43]
	v_mfma_f32_16x16x32_f16 a[28:31], v[0:3], v[16:19], a[28:31]
	v_mfma_f32_16x16x32_f16 a[20:23], v[4:7], v[16:19], a[20:23]
	v_mfma_f32_16x16x32_f16 a[12:15], v[8:11], v[16:19], a[12:15]
	v_mfma_f32_16x16x32_f16 a[4:7], v[12:15], v[16:19], a[4:7]
	s_addk_i32 s13, 0x80
	s_cmp_eq_u32 s13, 0x1c280
	s_cbranch_scc1 .LBB0_1633

; #define LD_BF(dst, ks_, nh_) _Pragma("unroll") for (int i = 0; i < 4; ++i) dst[i] = *(const h8*)(sB + ((nh_) * 4 + i) * 16 * G_LD + (ks_) * 32)
; #define MMA_BLK(afx, bfx, nh_) _Pragma("unroll") for (int mi = 0; mi < 8; ++mi) _Pragma("unroll") for (int ni = 0; ni < 4; ++ni) mfma16_acc(acc[mi][(nh_) * 4 + ni], bfx[ni], afx[mi])
; template <class Epi>
; __device__ __forceinline__ void gemm_run(const GemmArgs g, Epi epi, char* smem) {
;     ...
;       LD_BF(bfB, 1, 1);
;       MMA_BLK(afB, bfA, 0);
;       __builtin_amdgcn_sched_barrier(0);
;       MMA_BLK(afB, bfB, 1);
;       __builtin_amdgcn_sched_barrier(0);
;     ...
;       __syncthreads();
;     }
.LBB0_2022:
	ds_read_b128 v[0:3], v92 offset:46144
	ds_read_b128 v[4:7], v92 offset:48448
	ds_read_b128 v[8:11], v92 offset:50752
	ds_read_b128 v[12:15], v92 offset:53056
	s_waitcnt lgkmcnt(7)
	v_mfma_f32_16x16x32_f16 a[208:211], v[64:67], v[60:63], a[208:211]
	s_waitcnt lgkmcnt(6)
	v_mfma_f32_16x16x32_f16 a[200:203], v[68:71], v[60:63], a[200:203]
	s_waitcnt lgkmcnt(5)
	v_mfma_f32_16x16x32_f16 a[196:199], v[72:75], v[60:63], a[196:199]
	s_waitcnt lgkmcnt(4)
	v_mfma_f32_16x16x32_f16 a[192:195], v[76:79], v[60:63], a[192:195]
	v_mfma_f32_16x16x32_f16 a[188:191], v[64:67], v[52:55], a[188:191]
	v_mfma_f32_16x16x32_f16 a[184:187], v[68:71], v[52:55], a[184:187]
	v_mfma_f32_16x16x32_f16 a[180:183], v[72:75], v[52:55], a[180:183]
	v_mfma_f32_16x16x32_f16 a[176:179], v[76:79], v[52:55], a[176:179]
	v_mfma_f32_16x16x32_f16 a[156:159], v[64:67], v[48:51], a[156:159]
	v_mfma_f32_16x16x32_f16 a[152:155], v[68:71], v[48:51], a[152:155]
	v_mfma_f32_16x16x32_f16 a[148:151], v[72:75], v[48:51], a[148:151]
	v_mfma_f32_16x16x32_f16 a[144:147], v[76:79], v[48:51], a[144:147]
	v_mfma_f32_16x16x32_f16 a[124:127], v[64:67], v[40:43], a[124:127]
	v_mfma_f32_16x16x32_f16 a[120:123], v[68:71], v[40:43], a[120:123]
	v_mfma_f32_16x16x32_f16 a[116:119], v[72:75], v[40:43], a[116:119]
	v_mfma_f32_16x16x32_f16 a[112:115], v[76:79], v[40:43], a[112:115]
	v_mfma_f32_16x16x32_f16 a[92:95], v[64:67], v[36:39], a[92:95]
	v_mfma_f32_16x16x32_f16 a[88:91], v[68:71], v[36:39], a[88:91]
	v_mfma_f32_16x16x32_f16 a[84:87], v[72:75], v[36:39], a[84:87]
	v_mfma_f32_16x16x32_f16 a[80:83], v[76:79], v[36:39], a[80:83]
	v_mfma_f32_16x16x32_f16 a[60:63], v[64:67], v[32:35], a[60:63]
	v_mfma_f32_16x16x32_f16 a[56:59], v[68:71], v[32:35], a[56:59]
	v_mfma_f32_16x16x32_f16 a[52:55], v[72:75], v[32:35], a[52:55]
	v_mfma_f32_16x16x32_f16 a[48:51], v[76:79], v[32:35], a[48:51]
	v_mfma_f32_16x16x32_f16 a[28:31], v[64:67], v[24:27], a[28:31]
	v_mfma_f32_16x16x32_f16 a[24:27], v[68:71], v[24:27], a[24:27]
	v_mfma_f32_16x16x32_f16 a[20:23], v[72:75], v[24:27], a[20:23]
	v_mfma_f32_16x16x32_f16 a[16:19], v[76:79], v[24:27], a[16:19]
	v_mfma_f32_16x16x32_f16 a[12:15], v[64:67], v[16:19], a[12:15]
	v_mfma_f32_16x16x32_f16 a[8:11], v[68:71], v[16:19], a[8:11]
	v_mfma_f32_16x16x32_f16 a[4:7], v[72:75], v[16:19], a[4:7]
	v_mfma_f32_16x16x32_f16 a[0:3], v[76:79], v[16:19], a[0:3]
	s_waitcnt lgkmcnt(3)
	v_mfma_f32_16x16x32_f16 a[240:243], v[0:3], v[60:63], a[240:243]
	s_waitcnt lgkmcnt(2)
	v_mfma_f32_16x16x32_f16 a[252:255], v[4:7], v[60:63], a[252:255]
	s_waitcnt lgkmcnt(1)
	v_mfma_f32_16x16x32_f16 a[248:251], v[8:11], v[60:63], a[248:251]
	s_waitcnt lgkmcnt(0)
	s_barrier
	v_mfma_f32_16x16x32_f16 a[244:247], v[12:15], v[60:63], a[244:247]
	v_mfma_f32_16x16x32_f16 a[236:239], v[0:3], v[52:55], a[236:239]
	v_mfma_f32_16x16x32_f16 a[232:235], v[4:7], v[52:55], a[232:235]
	v_mfma_f32_16x16x32_f16 a[228:231], v[8:11], v[52:55], a[228:231]
	v_mfma_f32_16x16x32_f16 a[224:227], v[12:15], v[52:55], a[224:227]
	v_mfma_f32_16x16x32_f16 a[220:223], v[0:3], v[48:51], a[220:223]
	v_mfma_f32_16x16x32_f16 a[216:219], v[4:7], v[48:51], a[216:219]
	v_mfma_f32_16x16x32_f16 a[212:215], v[8:11], v[48:51], a[212:215]
	v_mfma_f32_16x16x32_f16 a[204:207], v[12:15], v[48:51], a[204:207]
	v_mfma_f32_16x16x32_f16 a[172:175], v[0:3], v[40:43], a[172:175]
	v_mfma_f32_16x16x32_f16 a[168:171], v[4:7], v[40:43], a[168:171]
	v_mfma_f32_16x16x32_f16 a[164:167], v[8:11], v[40:43], a[164:167]
	v_mfma_f32_16x16x32_f16 a[160:163], v[12:15], v[40:43], a[160:163]
	v_mfma_f32_16x16x32_f16 a[140:143], v[0:3], v[36:39], a[140:143]
	v_mfma_f32_16x16x32_f16 a[136:139], v[4:7], v[36:39], a[136:139]
	v_mfma_f32_16x16x32_f16 a[132:135], v[8:11], v[36:39], a[132:135]
	v_mfma_f32_16x16x32_f16 a[128:131], v[12:15], v[36:39], a[128:131]
	v_mfma_f32_16x16x32_f16 a[108:111], v[0:3], v[32:35], a[108:111]
	v_mfma_f32_16x16x32_f16 a[104:107], v[4:7], v[32:35], a[104:107]
	v_mfma_f32_16x16x32_f16 a[100:103], v[8:11], v[32:35], a[100:103]
	v_mfma_f32_16x16x32_f16 a[96:99], v[12:15], v[32:35], a[96:99]
	v_mfma_f32_16x16x32_f16 a[76:79], v[0:3], v[24:27], a[76:79]
	v_mfma_f32_16x16x32_f16 a[72:75], v[4:7], v[24:27], a[72:75]
	v_mfma_f32_16x16x32_f16 a[68:71], v[8:11], v[24:27], a[68:71]
	v_mfma_f32_16x16x32_f16 a[64:67], v[12:15], v[24:27], a[64:67]
	v_mfma_f32_16x16x32_f16 a[44:47], v[0:3], v[16:19], a[44:47]
	v_mfma_f32_16x16x32_f16 a[40:43], v[4:7], v[16:19], a[40:43]
	v_mfma_f32_16x16x32_f16 a[36:39], v[8:11], v[16:19], a[36:39]
	v_mfma_f32_16x16x32_f16 a[32:35], v[12:15], v[16:19], a[32:35]
	s_addk_i32 s21, 0x80
	s_cmp_eq_u32 s21, 0xe1080
	s_cbranch_scc1 .LBB0_2020

; #define LD_BF(dst, ks_, nh_) _Pragma("unroll") for (int i = 0; i < 4; ++i) dst[i] = *(const h8*)(sB + ((nh_) * 4 + i) * 16 * G_LD + (ks_) * 32)
; #define MMA_BLK(afx, bfx, nh_) _Pragma("unroll") for (int mi = 0; mi < 8; ++mi) _Pragma("unroll") for (int ni = 0; ni < 4; ++ni) mfma16_acc(acc[mi][(nh_) * 4 + ni], bfx[ni], afx[mi])
; template <class Epi>
; __device__ __forceinline__ void gemm_run(const GemmArgs g, Epi epi, char* smem) {
;     ...
;       LD_BF(bfB, 1, 1);
;       MMA_BLK(afB, bfA, 0);
;       __builtin_amdgcn_sched_barrier(0);
;       MMA_BLK(afB, bfB, 1);
;       __builtin_amdgcn_sched_barrier(0);
;     ...
;       __syncthreads();
;     }
.LBB0_2051:
	ds_read_b128 v[0:3], v106 offset:46144
	ds_read_b128 v[4:7], v106 offset:48448
	ds_read_b128 v[8:11], v106 offset:50752
	ds_read_b128 v[12:15], v106 offset:53056
	s_waitcnt lgkmcnt(7)
	v_mfma_f32_16x16x32_f16 a[120:123], v[64:67], v[60:63], a[120:123]
	s_waitcnt lgkmcnt(6)
	v_mfma_f32_16x16x32_f16 a[116:119], v[68:71], v[60:63], a[116:119]
	s_waitcnt lgkmcnt(5)
	v_mfma_f32_16x16x32_f16 a[112:115], v[72:75], v[60:63], a[112:115]
	s_waitcnt lgkmcnt(4)
	v_mfma_f32_16x16x32_f16 a[160:163], v[76:79], v[60:63], a[160:163]
	v_mfma_f32_16x16x32_f16 a[152:155], v[64:67], v[52:55], a[152:155]
	v_mfma_f32_16x16x32_f16 a[148:151], v[68:71], v[52:55], a[148:151]
	v_mfma_f32_16x16x32_f16 a[144:147], v[72:75], v[52:55], a[144:147]
	v_mfma_f32_16x16x32_f16 a[136:139], v[76:79], v[52:55], a[136:139]
	v_mfma_f32_16x16x32_f16 a[108:111], v[64:67], v[48:51], a[108:111]
	v_mfma_f32_16x16x32_f16 a[104:107], v[68:71], v[48:51], a[104:107]
	v_mfma_f32_16x16x32_f16 a[100:103], v[72:75], v[48:51], a[100:103]
	v_mfma_f32_16x16x32_f16 a[92:95], v[76:79], v[48:51], a[92:95]
	v_mfma_f32_16x16x32_f16 a[76:79], v[64:67], v[40:43], a[76:79]
	v_mfma_f32_16x16x32_f16 a[72:75], v[68:71], v[40:43], a[72:75]
	v_mfma_f32_16x16x32_f16 a[68:71], v[72:75], v[40:43], a[68:71]
	v_mfma_f32_16x16x32_f16 a[64:67], v[76:79], v[40:43], a[64:67]
	v_mfma_f32_16x16x32_f16 a[60:63], v[64:67], v[36:39], a[60:63]
	v_mfma_f32_16x16x32_f16 a[56:59], v[68:71], v[36:39], a[56:59]
	v_mfma_f32_16x16x32_f16 a[52:55], v[72:75], v[36:39], a[52:55]
	v_mfma_f32_16x16x32_f16 a[48:51], v[76:79], v[36:39], a[48:51]
	v_mfma_f32_16x16x32_f16 a[44:47], v[64:67], v[32:35], a[44:47]
	v_mfma_f32_16x16x32_f16 a[40:43], v[68:71], v[32:35], a[40:43]
	v_mfma_f32_16x16x32_f16 a[36:39], v[72:75], v[32:35], a[36:39]
	v_mfma_f32_16x16x32_f16 a[32:35], v[76:79], v[32:35], a[32:35]
	v_mfma_f32_16x16x32_f16 a[28:31], v[64:67], v[24:27], a[28:31]
	v_mfma_f32_16x16x32_f16 a[24:27], v[68:71], v[24:27], a[24:27]
	v_mfma_f32_16x16x32_f16 a[20:23], v[72:75], v[24:27], a[20:23]
	v_mfma_f32_16x16x32_f16 a[16:19], v[76:79], v[24:27], a[16:19]
	v_mfma_f32_16x16x32_f16 a[12:15], v[64:67], v[16:19], a[12:15]
	v_mfma_f32_16x16x32_f16 a[8:11], v[68:71], v[16:19], a[8:11]
	v_mfma_f32_16x16x32_f16 a[4:7], v[72:75], v[16:19], a[4:7]
	v_mfma_f32_16x16x32_f16 a[0:3], v[76:79], v[16:19], a[0:3]
	s_waitcnt lgkmcnt(3)
	v_mfma_f32_16x16x32_f16 a[252:255], v[0:3], v[60:63], a[252:255]
	s_waitcnt lgkmcnt(2)
	v_mfma_f32_16x16x32_f16 a[248:251], v[4:7], v[60:63], a[248:251]
	s_waitcnt lgkmcnt(1)
	v_mfma_f32_16x16x32_f16 a[244:247], v[8:11], v[60:63], a[244:247]
	s_waitcnt lgkmcnt(0)
	s_barrier
	v_mfma_f32_16x16x32_f16 a[240:243], v[12:15], v[60:63], a[240:243]
	v_mfma_f32_16x16x32_f16 a[236:239], v[0:3], v[52:55], a[236:239]
	v_mfma_f32_16x16x32_f16 a[232:235], v[4:7], v[52:55], a[232:235]
	v_mfma_f32_16x16x32_f16 a[228:231], v[8:11], v[52:55], a[228:231]
	v_mfma_f32_16x16x32_f16 a[224:227], v[12:15], v[52:55], a[224:227]
	v_mfma_f32_16x16x32_f16 a[220:223], v[0:3], v[48:51], a[220:223]
	v_mfma_f32_16x16x32_f16 a[216:219], v[4:7], v[48:51], a[216:219]
	v_mfma_f32_16x16x32_f16 a[212:215], v[8:11], v[48:51], a[212:215]
	v_mfma_f32_16x16x32_f16 a[208:211], v[12:15], v[48:51], a[208:211]
	v_mfma_f32_16x16x32_f16 a[204:207], v[0:3], v[40:43], a[204:207]
	v_mfma_f32_16x16x32_f16 a[200:203], v[4:7], v[40:43], a[200:203]
	v_mfma_f32_16x16x32_f16 a[196:199], v[8:11], v[40:43], a[196:199]
	v_mfma_f32_16x16x32_f16 a[192:195], v[12:15], v[40:43], a[192:195]
	v_mfma_f32_16x16x32_f16 a[188:191], v[0:3], v[36:39], a[188:191]
	v_mfma_f32_16x16x32_f16 a[184:187], v[4:7], v[36:39], a[184:187]
	v_mfma_f32_16x16x32_f16 a[180:183], v[8:11], v[36:39], a[180:183]
	v_mfma_f32_16x16x32_f16 a[176:179], v[12:15], v[36:39], a[176:179]
	v_mfma_f32_16x16x32_f16 a[172:175], v[0:3], v[32:35], a[172:175]
	v_mfma_f32_16x16x32_f16 a[168:171], v[4:7], v[32:35], a[168:171]
	v_mfma_f32_16x16x32_f16 a[164:167], v[8:11], v[32:35], a[164:167]
	v_mfma_f32_16x16x32_f16 a[156:159], v[12:15], v[32:35], a[156:159]
	v_mfma_f32_16x16x32_f16 a[140:143], v[0:3], v[24:27], a[140:143]
	v_mfma_f32_16x16x32_f16 a[132:135], v[4:7], v[24:27], a[132:135]
	v_mfma_f32_16x16x32_f16 a[128:131], v[8:11], v[24:27], a[128:131]
	v_mfma_f32_16x16x32_f16 a[124:127], v[12:15], v[24:27], a[124:127]
	v_mfma_f32_16x16x32_f16 a[96:99], v[0:3], v[16:19], a[96:99]
	v_mfma_f32_16x16x32_f16 a[88:91], v[4:7], v[16:19], a[88:91]
	v_mfma_f32_16x16x32_f16 a[84:87], v[8:11], v[16:19], a[84:87]
	v_mfma_f32_16x16x32_f16 a[80:83], v[12:15], v[16:19], a[80:83]
	s_addk_i32 s17, 0x80
	s_cmp_eq_u32 s17, 0xe1080
	s_cbranch_scc1 .LBB0_2054

; #define LD_BF(dst, ks_, nh_) _Pragma("unroll") for (int i = 0; i < 4; ++i) dst[i] = *(const h8*)(sB + ((nh_) * 4 + i) * 16 * G_LD + (ks_) * 32)
; #define MMA_BLK(afx, bfx, nh_) _Pragma("unroll") for (int mi = 0; mi < 8; ++mi) _Pragma("unroll") for (int ni = 0; ni < 4; ++ni) mfma16_acc(acc[mi][(nh_) * 4 + ni], bfx[ni], afx[mi])
; template <class Epi>
; __device__ __forceinline__ void gemm_run(const GemmArgs g, Epi epi, char* smem) {
;     ...
;       LD_BF(bfB, 1, 1);
;       MMA_BLK(afB, bfA, 0);
;       __builtin_amdgcn_sched_barrier(0);
;       MMA_BLK(afB, bfB, 1);
;       __builtin_amdgcn_sched_barrier(0);
;     ...
;       __syncthreads();
;     }
.LBB0_2102:
	ds_read_b128 v[0:3], v92 offset:46144
	ds_read_b128 v[4:7], v92 offset:48448
	ds_read_b128 v[8:11], v92 offset:50752
	ds_read_b128 v[12:15], v92 offset:53056
	s_waitcnt lgkmcnt(7)
	v_mfma_f32_16x16x32_f16 a[208:211], v[64:67], v[60:63], a[208:211]
	s_waitcnt lgkmcnt(6)
	v_mfma_f32_16x16x32_f16 a[200:203], v[68:71], v[60:63], a[200:203]
	s_waitcnt lgkmcnt(5)
	v_mfma_f32_16x16x32_f16 a[196:199], v[72:75], v[60:63], a[196:199]
	s_waitcnt lgkmcnt(4)
	v_mfma_f32_16x16x32_f16 a[192:195], v[76:79], v[60:63], a[192:195]
	v_mfma_f32_16x16x32_f16 a[188:191], v[64:67], v[52:55], a[188:191]
	v_mfma_f32_16x16x32_f16 a[184:187], v[68:71], v[52:55], a[184:187]
	v_mfma_f32_16x16x32_f16 a[180:183], v[72:75], v[52:55], a[180:183]
	v_mfma_f32_16x16x32_f16 a[176:179], v[76:79], v[52:55], a[176:179]
	v_mfma_f32_16x16x32_f16 a[156:159], v[64:67], v[48:51], a[156:159]
	v_mfma_f32_16x16x32_f16 a[152:155], v[68:71], v[48:51], a[152:155]
	v_mfma_f32_16x16x32_f16 a[148:151], v[72:75], v[48:51], a[148:151]
	v_mfma_f32_16x16x32_f16 a[144:147], v[76:79], v[48:51], a[144:147]
	v_mfma_f32_16x16x32_f16 a[124:127], v[64:67], v[40:43], a[124:127]
	v_mfma_f32_16x16x32_f16 a[120:123], v[68:71], v[40:43], a[120:123]
	v_mfma_f32_16x16x32_f16 a[116:119], v[72:75], v[40:43], a[116:119]
	v_mfma_f32_16x16x32_f16 a[112:115], v[76:79], v[40:43], a[112:115]
	v_mfma_f32_16x16x32_f16 a[92:95], v[64:67], v[36:39], a[92:95]
	v_mfma_f32_16x16x32_f16 a[88:91], v[68:71], v[36:39], a[88:91]
	v_mfma_f32_16x16x32_f16 a[84:87], v[72:75], v[36:39], a[84:87]
	v_mfma_f32_16x16x32_f16 a[80:83], v[76:79], v[36:39], a[80:83]
	v_mfma_f32_16x16x32_f16 a[60:63], v[64:67], v[32:35], a[60:63]
	v_mfma_f32_16x16x32_f16 a[56:59], v[68:71], v[32:35], a[56:59]
	v_mfma_f32_16x16x32_f16 a[52:55], v[72:75], v[32:35], a[52:55]
	v_mfma_f32_16x16x32_f16 a[48:51], v[76:79], v[32:35], a[48:51]
	v_mfma_f32_16x16x32_f16 a[28:31], v[64:67], v[24:27], a[28:31]
	v_mfma_f32_16x16x32_f16 a[24:27], v[68:71], v[24:27], a[24:27]
	v_mfma_f32_16x16x32_f16 a[20:23], v[72:75], v[24:27], a[20:23]
	v_mfma_f32_16x16x32_f16 a[16:19], v[76:79], v[24:27], a[16:19]
	v_mfma_f32_16x16x32_f16 a[12:15], v[64:67], v[16:19], a[12:15]
	v_mfma_f32_16x16x32_f16 a[8:11], v[68:71], v[16:19], a[8:11]
	v_mfma_f32_16x16x32_f16 a[4:7], v[72:75], v[16:19], a[4:7]
	v_mfma_f32_16x16x32_f16 a[0:3], v[76:79], v[16:19], a[0:3]
	s_waitcnt lgkmcnt(3)
	v_mfma_f32_16x16x32_f16 a[240:243], v[0:3], v[60:63], a[240:243]
	s_waitcnt lgkmcnt(2)
	v_mfma_f32_16x16x32_f16 a[252:255], v[4:7], v[60:63], a[252:255]
	s_waitcnt lgkmcnt(1)
	v_mfma_f32_16x16x32_f16 a[248:251], v[8:11], v[60:63], a[248:251]
	s_waitcnt lgkmcnt(0)
	s_barrier
	v_mfma_f32_16x16x32_f16 a[244:247], v[12:15], v[60:63], a[244:247]
	v_mfma_f32_16x16x32_f16 a[236:239], v[0:3], v[52:55], a[236:239]
	v_mfma_f32_16x16x32_f16 a[232:235], v[4:7], v[52:55], a[232:235]
	v_mfma_f32_16x16x32_f16 a[228:231], v[8:11], v[52:55], a[228:231]
	v_mfma_f32_16x16x32_f16 a[224:227], v[12:15], v[52:55], a[224:227]
	v_mfma_f32_16x16x32_f16 a[220:223], v[0:3], v[48:51], a[220:223]
	v_mfma_f32_16x16x32_f16 a[216:219], v[4:7], v[48:51], a[216:219]
	v_mfma_f32_16x16x32_f16 a[212:215], v[8:11], v[48:51], a[212:215]
	v_mfma_f32_16x16x32_f16 a[204:207], v[12:15], v[48:51], a[204:207]
	v_mfma_f32_16x16x32_f16 a[172:175], v[0:3], v[40:43], a[172:175]
	v_mfma_f32_16x16x32_f16 a[168:171], v[4:7], v[40:43], a[168:171]
	v_mfma_f32_16x16x32_f16 a[164:167], v[8:11], v[40:43], a[164:167]
	v_mfma_f32_16x16x32_f16 a[160:163], v[12:15], v[40:43], a[160:163]
	v_mfma_f32_16x16x32_f16 a[140:143], v[0:3], v[36:39], a[140:143]
	v_mfma_f32_16x16x32_f16 a[136:139], v[4:7], v[36:39], a[136:139]
	v_mfma_f32_16x16x32_f16 a[132:135], v[8:11], v[36:39], a[132:135]
	v_mfma_f32_16x16x32_f16 a[128:131], v[12:15], v[36:39], a[128:131]
	v_mfma_f32_16x16x32_f16 a[108:111], v[0:3], v[32:35], a[108:111]
	v_mfma_f32_16x16x32_f16 a[104:107], v[4:7], v[32:35], a[104:107]
	v_mfma_f32_16x16x32_f16 a[100:103], v[8:11], v[32:35], a[100:103]
	v_mfma_f32_16x16x32_f16 a[96:99], v[12:15], v[32:35], a[96:99]
	v_mfma_f32_16x16x32_f16 a[76:79], v[0:3], v[24:27], a[76:79]
	v_mfma_f32_16x16x32_f16 a[72:75], v[4:7], v[24:27], a[72:75]
	v_mfma_f32_16x16x32_f16 a[68:71], v[8:11], v[24:27], a[68:71]
	v_mfma_f32_16x16x32_f16 a[64:67], v[12:15], v[24:27], a[64:67]
	v_mfma_f32_16x16x32_f16 a[44:47], v[0:3], v[16:19], a[44:47]
	v_mfma_f32_16x16x32_f16 a[40:43], v[4:7], v[16:19], a[40:43]
	v_mfma_f32_16x16x32_f16 a[36:39], v[8:11], v[16:19], a[36:39]
	v_mfma_f32_16x16x32_f16 a[32:35], v[12:15], v[16:19], a[32:35]
	s_addk_i32 s54, 0x80
	s_cmp_eq_u32 s54, 0x26ac80
	s_cbranch_scc1 .LBB0_2100

; #define LD_BF(dst, ks_, nh_) _Pragma("unroll") for (int i = 0; i < 4; ++i) dst[i] = *(const h8*)(sB + ((nh_) * 4 + i) * 16 * G_LD + (ks_) * 32)
; #define MMA_BLK(afx, bfx, nh_) _Pragma("unroll") for (int mi = 0; mi < 8; ++mi) _Pragma("unroll") for (int ni = 0; ni < 4; ++ni) mfma16_acc(acc[mi][(nh_) * 4 + ni], bfx[ni], afx[mi])
; template <class Epi>
; __device__ __forceinline__ void gemm_run(const GemmArgs g, Epi epi, char* smem) {
;     ...
;       LD_BF(bfB, 1, 1);
;       MMA_BLK(afB, bfA, 0);
;       __builtin_amdgcn_sched_barrier(0);
;       MMA_BLK(afB, bfB, 1);
;       __builtin_amdgcn_sched_barrier(0);
;     ...
;       __syncthreads();
;     }
.LBB0_2108:
	ds_read_b128 v[0:3], v106 offset:46144
	ds_read_b128 v[4:7], v106 offset:48448
	ds_read_b128 v[8:11], v106 offset:50752
	ds_read_b128 v[12:15], v106 offset:53056
	s_waitcnt lgkmcnt(7)
	v_mfma_f32_16x16x32_f16 a[120:123], v[64:67], v[60:63], a[120:123]
	s_waitcnt lgkmcnt(6)
	v_mfma_f32_16x16x32_f16 a[116:119], v[68:71], v[60:63], a[116:119]
	s_waitcnt lgkmcnt(5)
	v_mfma_f32_16x16x32_f16 a[112:115], v[72:75], v[60:63], a[112:115]
	s_waitcnt lgkmcnt(4)
	v_mfma_f32_16x16x32_f16 a[160:163], v[76:79], v[60:63], a[160:163]
	v_mfma_f32_16x16x32_f16 a[152:155], v[64:67], v[52:55], a[152:155]
	v_mfma_f32_16x16x32_f16 a[148:151], v[68:71], v[52:55], a[148:151]
	v_mfma_f32_16x16x32_f16 a[144:147], v[72:75], v[52:55], a[144:147]
	v_mfma_f32_16x16x32_f16 a[136:139], v[76:79], v[52:55], a[136:139]
	v_mfma_f32_16x16x32_f16 a[108:111], v[64:67], v[48:51], a[108:111]
	v_mfma_f32_16x16x32_f16 a[104:107], v[68:71], v[48:51], a[104:107]
	v_mfma_f32_16x16x32_f16 a[100:103], v[72:75], v[48:51], a[100:103]
	v_mfma_f32_16x16x32_f16 a[92:95], v[76:79], v[48:51], a[92:95]
	v_mfma_f32_16x16x32_f16 a[76:79], v[64:67], v[40:43], a[76:79]
	v_mfma_f32_16x16x32_f16 a[72:75], v[68:71], v[40:43], a[72:75]
	v_mfma_f32_16x16x32_f16 a[68:71], v[72:75], v[40:43], a[68:71]
	v_mfma_f32_16x16x32_f16 a[64:67], v[76:79], v[40:43], a[64:67]
	v_mfma_f32_16x16x32_f16 a[60:63], v[64:67], v[36:39], a[60:63]
	v_mfma_f32_16x16x32_f16 a[56:59], v[68:71], v[36:39], a[56:59]
	v_mfma_f32_16x16x32_f16 a[52:55], v[72:75], v[36:39], a[52:55]
	v_mfma_f32_16x16x32_f16 a[48:51], v[76:79], v[36:39], a[48:51]
	v_mfma_f32_16x16x32_f16 a[44:47], v[64:67], v[32:35], a[44:47]
	v_mfma_f32_16x16x32_f16 a[40:43], v[68:71], v[32:35], a[40:43]
	v_mfma_f32_16x16x32_f16 a[36:39], v[72:75], v[32:35], a[36:39]
	v_mfma_f32_16x16x32_f16 a[32:35], v[76:79], v[32:35], a[32:35]
	v_mfma_f32_16x16x32_f16 a[28:31], v[64:67], v[24:27], a[28:31]
	v_mfma_f32_16x16x32_f16 a[24:27], v[68:71], v[24:27], a[24:27]
	v_mfma_f32_16x16x32_f16 a[20:23], v[72:75], v[24:27], a[20:23]
	v_mfma_f32_16x16x32_f16 a[16:19], v[76:79], v[24:27], a[16:19]
	v_mfma_f32_16x16x32_f16 a[12:15], v[64:67], v[16:19], a[12:15]
	v_mfma_f32_16x16x32_f16 a[8:11], v[68:71], v[16:19], a[8:11]
	v_mfma_f32_16x16x32_f16 a[4:7], v[72:75], v[16:19], a[4:7]
	v_mfma_f32_16x16x32_f16 a[0:3], v[76:79], v[16:19], a[0:3]
	s_waitcnt lgkmcnt(3)
	v_mfma_f32_16x16x32_f16 a[252:255], v[0:3], v[60:63], a[252:255]
	s_waitcnt lgkmcnt(2)
	v_mfma_f32_16x16x32_f16 a[248:251], v[4:7], v[60:63], a[248:251]
	s_waitcnt lgkmcnt(1)
	v_mfma_f32_16x16x32_f16 a[244:247], v[8:11], v[60:63], a[244:247]
	s_waitcnt lgkmcnt(0)
	s_barrier
	v_mfma_f32_16x16x32_f16 a[240:243], v[12:15], v[60:63], a[240:243]
	v_mfma_f32_16x16x32_f16 a[236:239], v[0:3], v[52:55], a[236:239]
	v_mfma_f32_16x16x32_f16 a[232:235], v[4:7], v[52:55], a[232:235]
	v_mfma_f32_16x16x32_f16 a[228:231], v[8:11], v[52:55], a[228:231]
	v_mfma_f32_16x16x32_f16 a[224:227], v[12:15], v[52:55], a[224:227]
	v_mfma_f32_16x16x32_f16 a[220:223], v[0:3], v[48:51], a[220:223]
	v_mfma_f32_16x16x32_f16 a[216:219], v[4:7], v[48:51], a[216:219]
	v_mfma_f32_16x16x32_f16 a[212:215], v[8:11], v[48:51], a[212:215]
	v_mfma_f32_16x16x32_f16 a[208:211], v[12:15], v[48:51], a[208:211]
	v_mfma_f32_16x16x32_f16 a[204:207], v[0:3], v[40:43], a[204:207]
	v_mfma_f32_16x16x32_f16 a[200:203], v[4:7], v[40:43], a[200:203]
	v_mfma_f32_16x16x32_f16 a[196:199], v[8:11], v[40:43], a[196:199]
	v_mfma_f32_16x16x32_f16 a[192:195], v[12:15], v[40:43], a[192:195]
	v_mfma_f32_16x16x32_f16 a[188:191], v[0:3], v[36:39], a[188:191]
	v_mfma_f32_16x16x32_f16 a[184:187], v[4:7], v[36:39], a[184:187]
	v_mfma_f32_16x16x32_f16 a[180:183], v[8:11], v[36:39], a[180:183]
	v_mfma_f32_16x16x32_f16 a[176:179], v[12:15], v[36:39], a[176:179]
	v_mfma_f32_16x16x32_f16 a[172:175], v[0:3], v[32:35], a[172:175]
	v_mfma_f32_16x16x32_f16 a[168:171], v[4:7], v[32:35], a[168:171]
	v_mfma_f32_16x16x32_f16 a[164:167], v[8:11], v[32:35], a[164:167]
	v_mfma_f32_16x16x32_f16 a[156:159], v[12:15], v[32:35], a[156:159]
	v_mfma_f32_16x16x32_f16 a[140:143], v[0:3], v[24:27], a[140:143]
	v_mfma_f32_16x16x32_f16 a[132:135], v[4:7], v[24:27], a[132:135]
	v_mfma_f32_16x16x32_f16 a[128:131], v[8:11], v[24:27], a[128:131]
	v_mfma_f32_16x16x32_f16 a[124:127], v[12:15], v[24:27], a[124:127]
	v_mfma_f32_16x16x32_f16 a[96:99], v[0:3], v[16:19], a[96:99]
	v_mfma_f32_16x16x32_f16 a[88:91], v[4:7], v[16:19], a[88:91]
	v_mfma_f32_16x16x32_f16 a[84:87], v[8:11], v[16:19], a[84:87]
	v_mfma_f32_16x16x32_f16 a[80:83], v[12:15], v[16:19], a[80:83]
	s_addk_i32 s1, 0x80
	s_cmp_eq_u32 s1, 0xe1080
	s_cbranch_scc1 .LBB0_2111
